# GEMM units: first K-iteration peeled with C=0 on the first MFMA of each accumulator, 128 accumulator-zeroing moves per unit removed (5 of 8 GEMM instances)
# speedup vs baseline: 1.0027x; 1.0027x over previous
.LBB0_36:
	s_add_u32 s34, s28, 0x100
	s_addc_u32 s35, s29, 0
	s_mov_b32 s79, -2
	s_waitcnt lgkmcnt(0)
	s_add_u32 s10, s24, 0x100
	s_addc_u32 s11, s25, 0
	s_add_i32 s0, 0, 0x10000
	s_cmpk_eq_i32 s79, 0x54
	s_cselect_b32 s31, s21, s11
	s_cselect_b32 s30, s20, s10
	s_cselect_b32 s29, s23, s35
	s_cselect_b32 s28, s22, s34
	s_add_i32 s59, 0, 0x14000
	v_add_u32_e32 v140, s0, v251
	v_add_u32_e32 v156, s59, v251
	ds_read_b128 v[124:127], v140
	ds_read_b128 v[128:131], v140 offset:1024
	ds_read_b128 v[132:135], v140 offset:2048
	ds_read_b128 v[140:143], v140 offset:3072
	ds_read_b128 v[144:147], v156
	ds_read_b128 v[148:151], v156 offset:1024
	ds_read_b128 v[152:155], v156 offset:2048
	ds_read_b128 v[156:159], v156 offset:3072
	v_lshl_add_u64 v[192:193], s[24:25], 0, v[214:215]
	s_add_i32 m0, s41, 0xc000
	ds_read_b128 v[160:163], v253
	ds_read_b128 v[164:167], v253 offset:1024
	ds_read_b128 v[168:171], v253 offset:2048
	ds_read_b128 v[172:175], v253 offset:3072
	ds_read_b128 v[176:179], v253 offset:4096
	ds_read_b128 v[180:183], v253 offset:5120
	ds_read_b128 v[184:187], v253 offset:6144
	ds_read_b128 v[188:191], v253 offset:7168
	global_load_lds_dwordx4 v[192:193], off
	v_lshl_add_u64 v[192:193], s[24:25], 0, v[216:217]
	s_add_i32 m0, s41, 0xe000
	s_nop 0
	global_load_lds_dwordx4 v[192:193], off
	s_waitcnt vmcnt(8)
	s_waitcnt lgkmcnt(0)
	s_barrier
	s_setprio 1
	s_waitcnt lgkmcnt(0)
	v_mfma_f32_16x16x32_bf16 v[136:139], v[124:127], v[160:163], 0
	v_mfma_f32_16x16x32_bf16 v[120:123], v[132:135], v[160:163], 0
	v_mfma_f32_16x16x32_bf16 v[116:119], v[124:127], v[168:171], 0
	v_mfma_f32_16x16x32_bf16 v[104:107], v[132:135], v[168:171], 0
	v_mfma_f32_16x16x32_bf16 v[100:103], v[124:127], v[176:179], 0
	v_mfma_f32_16x16x32_bf16 v[88:91], v[132:135], v[176:179], 0
	v_mfma_f32_16x16x32_bf16 v[84:87], v[124:127], v[184:187], 0
	v_mfma_f32_16x16x32_bf16 v[72:75], v[132:135], v[184:187], 0
	v_mfma_f32_16x16x32_bf16 v[136:139], v[128:131], v[164:167], v[136:139]
	v_mfma_f32_16x16x32_bf16 v[120:123], v[140:143], v[164:167], v[120:123]
	v_mfma_f32_16x16x32_bf16 v[116:119], v[128:131], v[172:175], v[116:119]
	v_mfma_f32_16x16x32_bf16 v[104:107], v[140:143], v[172:175], v[104:107]
	v_mfma_f32_16x16x32_bf16 v[100:103], v[128:131], v[180:183], v[100:103]
	v_mfma_f32_16x16x32_bf16 v[88:91], v[140:143], v[180:183], v[88:91]
	v_mfma_f32_16x16x32_bf16 v[84:87], v[128:131], v[188:191], v[84:87]
	v_mfma_f32_16x16x32_bf16 v[72:75], v[140:143], v[188:191], v[72:75]
	s_setprio 0
	s_setprio 1
	v_mfma_f32_16x16x32_bf16 v[112:115], v[144:147], v[160:163], 0
	v_mfma_f32_16x16x32_bf16 v[108:111], v[152:155], v[160:163], 0
	v_mfma_f32_16x16x32_bf16 v[96:99], v[144:147], v[168:171], 0
	v_mfma_f32_16x16x32_bf16 v[92:95], v[152:155], v[168:171], 0
	v_mfma_f32_16x16x32_bf16 v[80:83], v[144:147], v[176:179], 0
	v_mfma_f32_16x16x32_bf16 v[76:79], v[152:155], v[176:179], 0
	v_mfma_f32_16x16x32_bf16 v[68:71], v[144:147], v[184:187], 0
	v_mfma_f32_16x16x32_bf16 v[64:67], v[152:155], v[184:187], 0
	v_mfma_f32_16x16x32_bf16 v[112:115], v[148:151], v[164:167], v[112:115]
	v_mfma_f32_16x16x32_bf16 v[108:111], v[156:159], v[164:167], v[108:111]
	v_mfma_f32_16x16x32_bf16 v[96:99], v[148:151], v[172:175], v[96:99]
	v_mfma_f32_16x16x32_bf16 v[92:95], v[156:159], v[172:175], v[92:95]
	v_mfma_f32_16x16x32_bf16 v[80:83], v[148:151], v[180:183], v[80:83]
	v_mfma_f32_16x16x32_bf16 v[76:79], v[156:159], v[180:183], v[76:79]
	v_mfma_f32_16x16x32_bf16 v[68:71], v[148:151], v[188:191], v[68:71]
	v_mfma_f32_16x16x32_bf16 v[64:67], v[156:159], v[188:191], v[64:67]
	s_setprio 0
	s_barrier
	s_add_i32 s0, s0, s40
	v_lshl_add_u64 v[192:193], s[28:29], 0, v[198:199]
	s_mov_b32 m0, s0
	ds_read_b128 v[160:163], v253 offset:16384
	ds_read_b128 v[164:167], v253 offset:17408
	ds_read_b128 v[168:171], v253 offset:18432
	ds_read_b128 v[172:175], v253 offset:19456
	ds_read_b128 v[176:179], v253 offset:20480
	ds_read_b128 v[180:183], v253 offset:21504
	ds_read_b128 v[184:187], v253 offset:22528
	ds_read_b128 v[188:191], v253 offset:23552
	global_load_lds_dwordx4 v[192:193], off
	s_add_i32 m0, s0, 0x2000
	s_add_u32 s0, s28, 0x160000
	v_lshl_add_u64 v[194:195], s[28:29], 0, v[212:213]
	s_addc_u32 s1, s29, 0
	s_add_i32 s24, s59, s40
	global_load_lds_dwordx4 v[194:195], off
	v_lshl_add_u64 v[196:197], s[0:1], 0, v[198:199]
	s_mov_b32 m0, s24
	v_lshl_add_u64 v[218:219], s[30:31], 0, v[212:213]
	global_load_lds_dwordx4 v[196:197], off
	v_lshl_add_u64 v[196:197], s[0:1], 0, v[212:213]
	s_add_i32 m0, s24, 0x2000
	s_nop 0
	global_load_lds_dwordx4 v[196:197], off
	v_lshl_add_u64 v[196:197], s[30:31], 0, v[198:199]
	s_mov_b32 m0, s41
	s_nop 0
	global_load_lds_dwordx4 v[196:197], off
	s_mov_b32 m0, s42
	s_nop 0
	global_load_lds_dwordx4 v[218:219], off
	s_waitcnt vmcnt(8)
	s_waitcnt lgkmcnt(0)
	s_barrier
	s_setprio 1
	s_waitcnt lgkmcnt(0)
	v_mfma_f32_16x16x32_bf16 v[60:63], v[124:127], v[160:163], 0
	v_mfma_f32_16x16x32_bf16 v[56:59], v[132:135], v[160:163], 0
	v_mfma_f32_16x16x32_bf16 v[52:55], v[124:127], v[168:171], 0
	v_mfma_f32_16x16x32_bf16 v[40:43], v[132:135], v[168:171], 0
	v_mfma_f32_16x16x32_bf16 v[36:39], v[124:127], v[176:179], 0
	v_mfma_f32_16x16x32_bf16 v[24:27], v[132:135], v[176:179], 0
	v_mfma_f32_16x16x32_bf16 v[20:23], v[124:127], v[184:187], 0
	v_mfma_f32_16x16x32_bf16 v[8:11], v[132:135], v[184:187], 0
	v_mfma_f32_16x16x32_bf16 v[60:63], v[128:131], v[164:167], v[60:63]
	v_mfma_f32_16x16x32_bf16 v[56:59], v[140:143], v[164:167], v[56:59]
	v_mfma_f32_16x16x32_bf16 v[52:55], v[128:131], v[172:175], v[52:55]
	v_mfma_f32_16x16x32_bf16 v[40:43], v[140:143], v[172:175], v[40:43]
	v_mfma_f32_16x16x32_bf16 v[36:39], v[128:131], v[180:183], v[36:39]
	v_mfma_f32_16x16x32_bf16 v[24:27], v[140:143], v[180:183], v[24:27]
	v_mfma_f32_16x16x32_bf16 v[20:23], v[128:131], v[188:191], v[20:23]
	v_mfma_f32_16x16x32_bf16 v[8:11], v[140:143], v[188:191], v[8:11]
	s_setprio 0
	s_setprio 1
	v_mfma_f32_16x16x32_bf16 v[48:51], v[144:147], v[160:163], 0
	v_mfma_f32_16x16x32_bf16 v[44:47], v[152:155], v[160:163], 0
	v_mfma_f32_16x16x32_bf16 v[32:35], v[144:147], v[168:171], 0
	v_mfma_f32_16x16x32_bf16 v[28:31], v[152:155], v[168:171], 0
	v_mfma_f32_16x16x32_bf16 v[16:19], v[144:147], v[176:179], 0
	v_mfma_f32_16x16x32_bf16 v[12:15], v[152:155], v[176:179], 0
	v_mfma_f32_16x16x32_bf16 v[4:7], v[144:147], v[184:187], 0
	v_mfma_f32_16x16x32_bf16 v[0:3], v[152:155], v[184:187], 0
	v_mfma_f32_16x16x32_bf16 v[48:51], v[148:151], v[164:167], v[48:51]
	v_mfma_f32_16x16x32_bf16 v[44:47], v[156:159], v[164:167], v[44:47]
	v_mfma_f32_16x16x32_bf16 v[32:35], v[148:151], v[172:175], v[32:35]
	v_mfma_f32_16x16x32_bf16 v[28:31], v[156:159], v[172:175], v[28:31]
	v_mfma_f32_16x16x32_bf16 v[16:19], v[148:151], v[180:183], v[16:19]
	v_mfma_f32_16x16x32_bf16 v[12:15], v[156:159], v[180:183], v[12:15]
	v_mfma_f32_16x16x32_bf16 v[4:7], v[148:151], v[188:191], v[4:7]
	v_mfma_f32_16x16x32_bf16 v[0:3], v[156:159], v[188:191], v[0:3]
	s_setprio 0
	s_barrier
	s_add_i32 s24, 0, 0x18000
	s_add_i32 s25, 0, 0x1c000
	v_add_u32_e32 v140, s24, v251
	v_add_u32_e32 v156, s25, v251
	ds_read_b128 v[124:127], v140
	ds_read_b128 v[128:131], v140 offset:1024
	ds_read_b128 v[132:135], v140 offset:2048
	ds_read_b128 v[140:143], v140 offset:3072
	ds_read_b128 v[144:147], v156
	ds_read_b128 v[148:151], v156 offset:1024
	ds_read_b128 v[152:155], v156 offset:2048
	ds_read_b128 v[156:159], v156 offset:3072
	s_add_u32 s0, s30, 0x160000
	s_addc_u32 s1, s31, 0
	s_mov_b32 m0, s43
	v_lshl_add_u64 v[220:221], s[0:1], 0, v[198:199]
	ds_read_b128 v[160:163], v253 offset:32768
	ds_read_b128 v[164:167], v253 offset:33792
	ds_read_b128 v[168:171], v253 offset:34816
	ds_read_b128 v[172:175], v253 offset:35840
	ds_read_b128 v[176:179], v253 offset:36864
	ds_read_b128 v[180:183], v253 offset:37888
	ds_read_b128 v[184:187], v253 offset:38912
	ds_read_b128 v[188:191], v253 offset:39936
	global_load_lds_dwordx4 v[220:221], off
	v_lshl_add_u64 v[220:221], s[0:1], 0, v[212:213]
	s_mov_b32 m0, s46
	s_nop 0
	global_load_lds_dwordx4 v[220:221], off
	s_waitcnt vmcnt(8)
	s_waitcnt lgkmcnt(0)
	s_barrier
	s_setprio 1
	s_waitcnt lgkmcnt(0)
	v_mfma_f32_16x16x32_bf16 v[136:139], v[124:127], v[160:163], v[136:139]
	v_mfma_f32_16x16x32_bf16 v[120:123], v[132:135], v[160:163], v[120:123]
	v_mfma_f32_16x16x32_bf16 v[116:119], v[124:127], v[168:171], v[116:119]
	v_mfma_f32_16x16x32_bf16 v[104:107], v[132:135], v[168:171], v[104:107]
	v_mfma_f32_16x16x32_bf16 v[100:103], v[124:127], v[176:179], v[100:103]
	v_mfma_f32_16x16x32_bf16 v[88:91], v[132:135], v[176:179], v[88:91]
	v_mfma_f32_16x16x32_bf16 v[84:87], v[124:127], v[184:187], v[84:87]
	v_mfma_f32_16x16x32_bf16 v[72:75], v[132:135], v[184:187], v[72:75]
	v_mfma_f32_16x16x32_bf16 v[136:139], v[128:131], v[164:167], v[136:139]
	v_mfma_f32_16x16x32_bf16 v[120:123], v[140:143], v[164:167], v[120:123]
	v_mfma_f32_16x16x32_bf16 v[116:119], v[128:131], v[172:175], v[116:119]
	v_mfma_f32_16x16x32_bf16 v[104:107], v[140:143], v[172:175], v[104:107]
	v_mfma_f32_16x16x32_bf16 v[100:103], v[128:131], v[180:183], v[100:103]
	v_mfma_f32_16x16x32_bf16 v[88:91], v[140:143], v[180:183], v[88:91]
	v_mfma_f32_16x16x32_bf16 v[84:87], v[128:131], v[188:191], v[84:87]
	v_mfma_f32_16x16x32_bf16 v[72:75], v[140:143], v[188:191], v[72:75]
	s_setprio 0
	s_setprio 1
	v_mfma_f32_16x16x32_bf16 v[112:115], v[144:147], v[160:163], v[112:115]
	v_mfma_f32_16x16x32_bf16 v[108:111], v[152:155], v[160:163], v[108:111]
	v_mfma_f32_16x16x32_bf16 v[96:99], v[144:147], v[168:171], v[96:99]
	v_mfma_f32_16x16x32_bf16 v[92:95], v[152:155], v[168:171], v[92:95]
	v_mfma_f32_16x16x32_bf16 v[80:83], v[144:147], v[176:179], v[80:83]
	v_mfma_f32_16x16x32_bf16 v[76:79], v[152:155], v[176:179], v[76:79]
	v_mfma_f32_16x16x32_bf16 v[68:71], v[144:147], v[184:187], v[68:71]
	v_mfma_f32_16x16x32_bf16 v[64:67], v[152:155], v[184:187], v[64:67]
	v_mfma_f32_16x16x32_bf16 v[112:115], v[148:151], v[164:167], v[112:115]
	v_mfma_f32_16x16x32_bf16 v[108:111], v[156:159], v[164:167], v[108:111]
	v_mfma_f32_16x16x32_bf16 v[96:99], v[148:151], v[172:175], v[96:99]
	v_mfma_f32_16x16x32_bf16 v[92:95], v[156:159], v[172:175], v[92:95]
	v_mfma_f32_16x16x32_bf16 v[80:83], v[148:151], v[180:183], v[80:83]
	v_mfma_f32_16x16x32_bf16 v[76:79], v[156:159], v[180:183], v[76:79]
	v_mfma_f32_16x16x32_bf16 v[68:71], v[148:151], v[188:191], v[68:71]
	v_mfma_f32_16x16x32_bf16 v[64:67], v[156:159], v[188:191], v[64:67]
	s_setprio 0
	s_barrier
	s_add_i32 s0, s24, s40
	v_lshl_add_u64 v[192:193], v[192:193], 0, s[54:55]
	s_mov_b32 m0, s0
	ds_read_b128 v[160:163], v253 offset:49152
	ds_read_b128 v[164:167], v253 offset:50176
	ds_read_b128 v[168:171], v253 offset:51200
	ds_read_b128 v[172:175], v253 offset:52224
	ds_read_b128 v[176:179], v253 offset:53248
	ds_read_b128 v[180:183], v253 offset:54272
	ds_read_b128 v[184:187], v253 offset:55296
	ds_read_b128 v[188:191], v253 offset:56320
	global_load_lds_dwordx4 v[192:193], off
	s_add_i32 m0, s0, 0x2000
	s_add_u32 s0, s28, 0x160080
	v_lshl_add_u64 v[192:193], v[194:195], 0, s[54:55]
	s_addc_u32 s1, s29, 0
	s_add_i32 s24, s25, s40
	global_load_lds_dwordx4 v[192:193], off
	v_lshl_add_u64 v[192:193], s[0:1], 0, v[198:199]
	s_mov_b32 m0, s24
	s_nop 0
	global_load_lds_dwordx4 v[192:193], off
	v_lshl_add_u64 v[192:193], s[0:1], 0, v[212:213]
	s_add_i32 m0, s24, 0x2000
	s_nop 0
	global_load_lds_dwordx4 v[192:193], off
	v_lshl_add_u64 v[192:193], v[196:197], 0, s[54:55]
	s_mov_b32 m0, s47
	s_nop 0
	global_load_lds_dwordx4 v[192:193], off
	v_lshl_add_u64 v[192:193], v[218:219], 0, s[54:55]
	s_mov_b32 m0, s48
	s_nop 0
	global_load_lds_dwordx4 v[192:193], off
	s_waitcnt vmcnt(8)
	s_waitcnt lgkmcnt(0)
	s_barrier
	s_setprio 1
	s_waitcnt lgkmcnt(0)
	v_mfma_f32_16x16x32_bf16 v[60:63], v[124:127], v[160:163], v[60:63]
	v_mfma_f32_16x16x32_bf16 v[56:59], v[132:135], v[160:163], v[56:59]
	v_mfma_f32_16x16x32_bf16 v[52:55], v[124:127], v[168:171], v[52:55]
	v_mfma_f32_16x16x32_bf16 v[40:43], v[132:135], v[168:171], v[40:43]
	v_mfma_f32_16x16x32_bf16 v[36:39], v[124:127], v[176:179], v[36:39]
	v_mfma_f32_16x16x32_bf16 v[24:27], v[132:135], v[176:179], v[24:27]
	v_mfma_f32_16x16x32_bf16 v[20:23], v[124:127], v[184:187], v[20:23]
	v_mfma_f32_16x16x32_bf16 v[8:11], v[132:135], v[184:187], v[8:11]
	v_mfma_f32_16x16x32_bf16 v[60:63], v[128:131], v[164:167], v[60:63]
	v_mfma_f32_16x16x32_bf16 v[56:59], v[140:143], v[164:167], v[56:59]
	v_mfma_f32_16x16x32_bf16 v[52:55], v[128:131], v[172:175], v[52:55]
	v_mfma_f32_16x16x32_bf16 v[40:43], v[140:143], v[172:175], v[40:43]
	v_mfma_f32_16x16x32_bf16 v[36:39], v[128:131], v[180:183], v[36:39]
	v_mfma_f32_16x16x32_bf16 v[24:27], v[140:143], v[180:183], v[24:27]
	v_mfma_f32_16x16x32_bf16 v[20:23], v[128:131], v[188:191], v[20:23]
	v_mfma_f32_16x16x32_bf16 v[8:11], v[140:143], v[188:191], v[8:11]
	s_setprio 0
	s_setprio 1
	v_mfma_f32_16x16x32_bf16 v[48:51], v[144:147], v[160:163], v[48:51]
	v_mfma_f32_16x16x32_bf16 v[44:47], v[152:155], v[160:163], v[44:47]
	v_mfma_f32_16x16x32_bf16 v[32:35], v[144:147], v[168:171], v[32:35]
	v_mfma_f32_16x16x32_bf16 v[28:31], v[152:155], v[168:171], v[28:31]
	v_mfma_f32_16x16x32_bf16 v[16:19], v[144:147], v[176:179], v[16:19]
	v_mfma_f32_16x16x32_bf16 v[12:15], v[152:155], v[176:179], v[12:15]
	v_mfma_f32_16x16x32_bf16 v[4:7], v[144:147], v[184:187], v[4:7]
	v_mfma_f32_16x16x32_bf16 v[0:3], v[152:155], v[184:187], v[0:3]
	v_mfma_f32_16x16x32_bf16 v[48:51], v[148:151], v[164:167], v[48:51]
	v_mfma_f32_16x16x32_bf16 v[44:47], v[156:159], v[164:167], v[44:47]
	v_mfma_f32_16x16x32_bf16 v[32:35], v[148:151], v[172:175], v[32:35]
	v_mfma_f32_16x16x32_bf16 v[28:31], v[156:159], v[172:175], v[28:31]
	v_mfma_f32_16x16x32_bf16 v[16:19], v[148:151], v[180:183], v[16:19]
	v_mfma_f32_16x16x32_bf16 v[12:15], v[156:159], v[180:183], v[12:15]
	v_mfma_f32_16x16x32_bf16 v[4:7], v[148:151], v[188:191], v[4:7]
	v_mfma_f32_16x16x32_bf16 v[0:3], v[156:159], v[188:191], v[0:3]
	s_setprio 0
	s_barrier
	s_add_i32 s79, s79, 2
	s_add_u32 s34, s34, 0x100
	s_addc_u32 s35, s35, 0
	s_mov_b64 s[24:25], s[10:11]

.LBB0_102:
	s_ashr_i32 s17, s16, 31
	s_lshl_b64 s[0:1], s[16:17], 20
	s_add_u32 s18, s26, s0
	s_addc_u32 s19, s27, s1
	s_and_b64 s[0:1], s[6:7], exec
	s_cselect_b32 s17, s19, s25
	s_cselect_b32 s51, s18, s24
	s_ashr_i32 s15, s14, 31
	s_lshl_b64 s[0:1], s[14:15], 20
	s_add_u32 s20, s36, s0
	s_addc_u32 s21, s37, s1
	s_and_b64 s[0:1], s[6:7], exec
	s_cselect_b32 s15, s21, s29
	s_cselect_b32 s34, s20, s28
	s_add_u32 s24, s24, 0x80080
	s_addc_u32 s25, s25, 0
	s_add_u32 s35, s28, 0x100
	s_addc_u32 s52, s29, 0
	s_mov_b32 s61, -2
	s_add_u32 s0, s24, 0xfff80080
	s_addc_u32 s1, s25, -1
	s_add_i32 s59, 0, 0x10000
	s_cmp_eq_u32 s61, 28
	s_cselect_b32 s31, s17, s1
	s_cselect_b32 s30, s51, s0
	s_cselect_b32 s29, s15, s52
	s_cselect_b32 s28, s34, s35
	s_add_i32 s63, 0, 0x14000
	v_add_u32_e32 v154, s59, v147
	v_add_u32_e32 v170, s63, v147
	ds_read_b128 v[138:141], v154
	ds_read_b128 v[142:145], v154 offset:1024
	ds_read_b128 v[150:153], v154 offset:2048
	ds_read_b128 v[154:157], v154 offset:3072
	ds_read_b128 v[158:161], v170
	ds_read_b128 v[162:165], v170 offset:1024
	ds_read_b128 v[166:169], v170 offset:2048
	ds_read_b128 v[170:173], v170 offset:3072
	v_lshl_add_u64 v[220:221], s[24:25], 0, v[134:135]
	s_add_i32 m0, s40, 0xc000
	ds_read_b128 v[174:177], v149
	ds_read_b128 v[178:181], v149 offset:1024
	ds_read_b128 v[182:185], v149 offset:2048
	ds_read_b128 v[186:189], v149 offset:3072
	ds_read_b128 v[190:193], v149 offset:4096
	ds_read_b128 v[194:197], v149 offset:5120
	ds_read_b128 v[212:215], v149 offset:6144
	ds_read_b128 v[216:219], v149 offset:7168
	global_load_lds_dwordx4 v[220:221], off
	v_lshl_add_u64 v[220:221], s[24:25], 0, v[136:137]
	s_add_i32 m0, s40, 0xe000
	s_nop 0
	global_load_lds_dwordx4 v[220:221], off
	s_waitcnt vmcnt(8)
	s_waitcnt lgkmcnt(0)
	s_barrier
	s_setprio 1
	s_waitcnt lgkmcnt(0)
	v_mfma_f32_16x16x32_bf16 v[124:127], v[138:141], v[174:177], 0
	v_mfma_f32_16x16x32_bf16 v[116:119], v[150:153], v[174:177], 0
	v_mfma_f32_16x16x32_bf16 v[108:111], v[138:141], v[182:185], 0
	v_mfma_f32_16x16x32_bf16 v[96:99], v[150:153], v[182:185], 0
	v_mfma_f32_16x16x32_bf16 v[88:91], v[138:141], v[190:193], 0
	v_mfma_f32_16x16x32_bf16 v[80:83], v[150:153], v[190:193], 0
	v_mfma_f32_16x16x32_bf16 v[72:75], v[138:141], v[212:215], 0
	v_mfma_f32_16x16x32_bf16 v[64:67], v[150:153], v[212:215], 0
	v_mfma_f32_16x16x32_bf16 v[124:127], v[142:145], v[178:181], v[124:127]
	v_mfma_f32_16x16x32_bf16 v[116:119], v[154:157], v[178:181], v[116:119]
	v_mfma_f32_16x16x32_bf16 v[108:111], v[142:145], v[186:189], v[108:111]
	v_mfma_f32_16x16x32_bf16 v[96:99], v[154:157], v[186:189], v[96:99]
	v_mfma_f32_16x16x32_bf16 v[88:91], v[142:145], v[194:197], v[88:91]
	v_mfma_f32_16x16x32_bf16 v[80:83], v[154:157], v[194:197], v[80:83]
	v_mfma_f32_16x16x32_bf16 v[72:75], v[142:145], v[216:219], v[72:75]
	v_mfma_f32_16x16x32_bf16 v[64:67], v[154:157], v[216:219], v[64:67]
	s_setprio 0
	s_setprio 1
	v_mfma_f32_16x16x32_bf16 v[120:123], v[158:161], v[174:177], 0
	v_mfma_f32_16x16x32_bf16 v[112:115], v[166:169], v[174:177], 0
	v_mfma_f32_16x16x32_bf16 v[104:107], v[158:161], v[182:185], 0
	v_mfma_f32_16x16x32_bf16 v[100:103], v[166:169], v[182:185], 0
	v_mfma_f32_16x16x32_bf16 v[92:95], v[158:161], v[190:193], 0
	v_mfma_f32_16x16x32_bf16 v[84:87], v[166:169], v[190:193], 0
	v_mfma_f32_16x16x32_bf16 v[76:79], v[158:161], v[212:215], 0
	v_mfma_f32_16x16x32_bf16 v[68:71], v[166:169], v[212:215], 0
	v_mfma_f32_16x16x32_bf16 v[120:123], v[162:165], v[178:181], v[120:123]
	v_mfma_f32_16x16x32_bf16 v[112:115], v[170:173], v[178:181], v[112:115]
	v_mfma_f32_16x16x32_bf16 v[104:107], v[162:165], v[186:189], v[104:107]
	v_mfma_f32_16x16x32_bf16 v[100:103], v[170:173], v[186:189], v[100:103]
	v_mfma_f32_16x16x32_bf16 v[92:95], v[162:165], v[194:197], v[92:95]
	v_mfma_f32_16x16x32_bf16 v[84:87], v[170:173], v[194:197], v[84:87]
	v_mfma_f32_16x16x32_bf16 v[76:79], v[162:165], v[216:219], v[76:79]
	v_mfma_f32_16x16x32_bf16 v[68:71], v[170:173], v[216:219], v[68:71]
	s_setprio 0
	s_barrier
	s_add_i32 s0, s59, s38
	v_lshl_add_u64 v[220:221], s[28:29], 0, v[198:199]
	s_mov_b32 m0, s0
	ds_read_b128 v[174:177], v149 offset:16384
	ds_read_b128 v[178:181], v149 offset:17408
	ds_read_b128 v[182:185], v149 offset:18432
	ds_read_b128 v[186:189], v149 offset:19456
	ds_read_b128 v[190:193], v149 offset:20480
	ds_read_b128 v[194:197], v149 offset:21504
	ds_read_b128 v[212:215], v149 offset:22528
	ds_read_b128 v[216:219], v149 offset:23552
	global_load_lds_dwordx4 v[220:221], off
	s_add_i32 m0, s0, 0x2000
	s_add_u32 s0, s28, 0x80000
	v_lshl_add_u64 v[222:223], s[28:29], 0, v[128:129]
	s_addc_u32 s1, s29, 0
	s_add_i32 s59, s63, s38
	global_load_lds_dwordx4 v[222:223], off
	v_lshl_add_u64 v[224:225], s[0:1], 0, v[198:199]
	s_mov_b32 m0, s59
	v_lshl_add_u64 v[226:227], s[30:31], 0, v[130:131]
	global_load_lds_dwordx4 v[224:225], off
	v_lshl_add_u64 v[224:225], s[0:1], 0, v[128:129]
	s_add_i32 m0, s59, 0x2000
	s_nop 0
	global_load_lds_dwordx4 v[224:225], off
	v_lshl_add_u64 v[224:225], s[30:31], 0, v[132:133]
	s_mov_b32 m0, s40
	s_nop 0
	global_load_lds_dwordx4 v[224:225], off
	s_mov_b32 m0, s41
	s_nop 0
	global_load_lds_dwordx4 v[226:227], off
	s_waitcnt vmcnt(8)
	s_waitcnt lgkmcnt(0)
	s_barrier
	s_setprio 1
	s_waitcnt lgkmcnt(0)
	v_mfma_f32_16x16x32_bf16 v[56:59], v[138:141], v[174:177], 0
	v_mfma_f32_16x16x32_bf16 v[48:51], v[150:153], v[174:177], 0
	v_mfma_f32_16x16x32_bf16 v[40:43], v[138:141], v[182:185], 0
	v_mfma_f32_16x16x32_bf16 v[32:35], v[150:153], v[182:185], 0
	v_mfma_f32_16x16x32_bf16 v[24:27], v[138:141], v[190:193], 0
	v_mfma_f32_16x16x32_bf16 v[16:19], v[150:153], v[190:193], 0
	v_mfma_f32_16x16x32_bf16 v[8:11], v[138:141], v[212:215], 0
	v_mfma_f32_16x16x32_bf16 v[0:3], v[150:153], v[212:215], 0
	v_mfma_f32_16x16x32_bf16 v[56:59], v[142:145], v[178:181], v[56:59]
	v_mfma_f32_16x16x32_bf16 v[48:51], v[154:157], v[178:181], v[48:51]
	v_mfma_f32_16x16x32_bf16 v[40:43], v[142:145], v[186:189], v[40:43]
	v_mfma_f32_16x16x32_bf16 v[32:35], v[154:157], v[186:189], v[32:35]
	v_mfma_f32_16x16x32_bf16 v[24:27], v[142:145], v[194:197], v[24:27]
	v_mfma_f32_16x16x32_bf16 v[16:19], v[154:157], v[194:197], v[16:19]
	v_mfma_f32_16x16x32_bf16 v[8:11], v[142:145], v[216:219], v[8:11]
	v_mfma_f32_16x16x32_bf16 v[0:3], v[154:157], v[216:219], v[0:3]
	s_setprio 0
	s_setprio 1
	v_mfma_f32_16x16x32_bf16 v[60:63], v[158:161], v[174:177], 0
	v_mfma_f32_16x16x32_bf16 v[52:55], v[166:169], v[174:177], 0
	v_mfma_f32_16x16x32_bf16 v[44:47], v[158:161], v[182:185], 0
	v_mfma_f32_16x16x32_bf16 v[36:39], v[166:169], v[182:185], 0
	v_mfma_f32_16x16x32_bf16 v[28:31], v[158:161], v[190:193], 0
	v_mfma_f32_16x16x32_bf16 v[20:23], v[166:169], v[190:193], 0
	v_mfma_f32_16x16x32_bf16 v[12:15], v[158:161], v[212:215], 0
	v_mfma_f32_16x16x32_bf16 v[4:7], v[166:169], v[212:215], 0
	v_mfma_f32_16x16x32_bf16 v[60:63], v[162:165], v[178:181], v[60:63]
	v_mfma_f32_16x16x32_bf16 v[52:55], v[170:173], v[178:181], v[52:55]
	v_mfma_f32_16x16x32_bf16 v[44:47], v[162:165], v[186:189], v[44:47]
	v_mfma_f32_16x16x32_bf16 v[36:39], v[170:173], v[186:189], v[36:39]
	v_mfma_f32_16x16x32_bf16 v[28:31], v[162:165], v[194:197], v[28:31]
	v_mfma_f32_16x16x32_bf16 v[20:23], v[170:173], v[194:197], v[20:23]
	v_mfma_f32_16x16x32_bf16 v[12:15], v[162:165], v[216:219], v[12:15]
	v_mfma_f32_16x16x32_bf16 v[4:7], v[170:173], v[216:219], v[4:7]
	s_setprio 0
	s_barrier
	s_add_i32 s59, 0, 0x18000
	s_add_i32 s63, 0, 0x1c000
	v_add_u32_e32 v154, s59, v147
	v_add_u32_e32 v170, s63, v147
	ds_read_b128 v[138:141], v154
	ds_read_b128 v[142:145], v154 offset:1024
	ds_read_b128 v[150:153], v154 offset:2048
	ds_read_b128 v[154:157], v154 offset:3072
	ds_read_b128 v[158:161], v170
	ds_read_b128 v[162:165], v170 offset:1024
	ds_read_b128 v[166:169], v170 offset:2048
	ds_read_b128 v[170:173], v170 offset:3072
	s_add_u32 s0, s30, 0x80000
	s_addc_u32 s1, s31, 0
	s_mov_b32 m0, s42
	v_lshl_add_u64 v[228:229], s[0:1], 0, v[132:133]
	ds_read_b128 v[174:177], v149 offset:32768
	ds_read_b128 v[178:181], v149 offset:33792
	ds_read_b128 v[182:185], v149 offset:34816
	ds_read_b128 v[186:189], v149 offset:35840
	ds_read_b128 v[190:193], v149 offset:36864
	ds_read_b128 v[194:197], v149 offset:37888
	ds_read_b128 v[212:215], v149 offset:38912
	ds_read_b128 v[216:219], v149 offset:39936
	global_load_lds_dwordx4 v[228:229], off
	v_lshl_add_u64 v[228:229], s[0:1], 0, v[130:131]
	s_mov_b32 m0, s43
	s_nop 0
	global_load_lds_dwordx4 v[228:229], off
	s_waitcnt vmcnt(8)
	s_waitcnt lgkmcnt(0)
	s_barrier
	s_setprio 1
	s_waitcnt lgkmcnt(0)
	v_mfma_f32_16x16x32_bf16 v[124:127], v[138:141], v[174:177], v[124:127]
	v_mfma_f32_16x16x32_bf16 v[116:119], v[150:153], v[174:177], v[116:119]
	v_mfma_f32_16x16x32_bf16 v[108:111], v[138:141], v[182:185], v[108:111]
	v_mfma_f32_16x16x32_bf16 v[96:99], v[150:153], v[182:185], v[96:99]
	v_mfma_f32_16x16x32_bf16 v[88:91], v[138:141], v[190:193], v[88:91]
	v_mfma_f32_16x16x32_bf16 v[80:83], v[150:153], v[190:193], v[80:83]
	v_mfma_f32_16x16x32_bf16 v[72:75], v[138:141], v[212:215], v[72:75]
	v_mfma_f32_16x16x32_bf16 v[64:67], v[150:153], v[212:215], v[64:67]
	v_mfma_f32_16x16x32_bf16 v[124:127], v[142:145], v[178:181], v[124:127]
	v_mfma_f32_16x16x32_bf16 v[116:119], v[154:157], v[178:181], v[116:119]
	v_mfma_f32_16x16x32_bf16 v[108:111], v[142:145], v[186:189], v[108:111]
	v_mfma_f32_16x16x32_bf16 v[96:99], v[154:157], v[186:189], v[96:99]
	v_mfma_f32_16x16x32_bf16 v[88:91], v[142:145], v[194:197], v[88:91]
	v_mfma_f32_16x16x32_bf16 v[80:83], v[154:157], v[194:197], v[80:83]
	v_mfma_f32_16x16x32_bf16 v[72:75], v[142:145], v[216:219], v[72:75]
	v_mfma_f32_16x16x32_bf16 v[64:67], v[154:157], v[216:219], v[64:67]
	s_setprio 0
	s_setprio 1
	v_mfma_f32_16x16x32_bf16 v[120:123], v[158:161], v[174:177], v[120:123]
	v_mfma_f32_16x16x32_bf16 v[112:115], v[166:169], v[174:177], v[112:115]
	v_mfma_f32_16x16x32_bf16 v[104:107], v[158:161], v[182:185], v[104:107]
	v_mfma_f32_16x16x32_bf16 v[100:103], v[166:169], v[182:185], v[100:103]
	v_mfma_f32_16x16x32_bf16 v[92:95], v[158:161], v[190:193], v[92:95]
	v_mfma_f32_16x16x32_bf16 v[84:87], v[166:169], v[190:193], v[84:87]
	v_mfma_f32_16x16x32_bf16 v[76:79], v[158:161], v[212:215], v[76:79]
	v_mfma_f32_16x16x32_bf16 v[68:71], v[166:169], v[212:215], v[68:71]
	v_mfma_f32_16x16x32_bf16 v[120:123], v[162:165], v[178:181], v[120:123]
	v_mfma_f32_16x16x32_bf16 v[112:115], v[170:173], v[178:181], v[112:115]
	v_mfma_f32_16x16x32_bf16 v[104:107], v[162:165], v[186:189], v[104:107]
	v_mfma_f32_16x16x32_bf16 v[100:103], v[170:173], v[186:189], v[100:103]
	v_mfma_f32_16x16x32_bf16 v[92:95], v[162:165], v[194:197], v[92:95]
	v_mfma_f32_16x16x32_bf16 v[84:87], v[170:173], v[194:197], v[84:87]
	v_mfma_f32_16x16x32_bf16 v[76:79], v[162:165], v[216:219], v[76:79]
	v_mfma_f32_16x16x32_bf16 v[68:71], v[170:173], v[216:219], v[68:71]
	s_setprio 0
	s_barrier
	s_add_i32 s0, s59, s38
	v_lshl_add_u64 v[220:221], v[220:221], 0, s[54:55]
	s_mov_b32 m0, s0
	ds_read_b128 v[174:177], v149 offset:49152
	ds_read_b128 v[178:181], v149 offset:50176
	ds_read_b128 v[182:185], v149 offset:51200
	ds_read_b128 v[186:189], v149 offset:52224
	ds_read_b128 v[190:193], v149 offset:53248
	ds_read_b128 v[194:197], v149 offset:54272
	ds_read_b128 v[212:215], v149 offset:55296
	ds_read_b128 v[216:219], v149 offset:56320
	global_load_lds_dwordx4 v[220:221], off
	s_add_i32 m0, s0, 0x2000
	s_add_u32 s0, s28, 0x80080
	v_lshl_add_u64 v[220:221], v[222:223], 0, s[54:55]
	s_addc_u32 s1, s29, 0
	s_add_i32 s28, s63, s38
	global_load_lds_dwordx4 v[220:221], off
	v_lshl_add_u64 v[220:221], s[0:1], 0, v[198:199]
	s_mov_b32 m0, s28
	s_nop 0
	global_load_lds_dwordx4 v[220:221], off
	v_lshl_add_u64 v[220:221], s[0:1], 0, v[128:129]
	s_add_i32 m0, s28, 0x2000
	s_nop 0
	global_load_lds_dwordx4 v[220:221], off
	v_lshl_add_u64 v[220:221], v[224:225], 0, s[54:55]
	s_mov_b32 m0, s47
	s_nop 0
	global_load_lds_dwordx4 v[220:221], off
	v_lshl_add_u64 v[220:221], v[226:227], 0, s[54:55]
	s_mov_b32 m0, s48
	s_nop 0
	global_load_lds_dwordx4 v[220:221], off
	s_waitcnt vmcnt(8)
	s_waitcnt lgkmcnt(0)
	s_barrier
	s_setprio 1
	s_waitcnt lgkmcnt(0)
	v_mfma_f32_16x16x32_bf16 v[56:59], v[138:141], v[174:177], v[56:59]
	v_mfma_f32_16x16x32_bf16 v[48:51], v[150:153], v[174:177], v[48:51]
	v_mfma_f32_16x16x32_bf16 v[40:43], v[138:141], v[182:185], v[40:43]
	v_mfma_f32_16x16x32_bf16 v[32:35], v[150:153], v[182:185], v[32:35]
	v_mfma_f32_16x16x32_bf16 v[24:27], v[138:141], v[190:193], v[24:27]
	v_mfma_f32_16x16x32_bf16 v[16:19], v[150:153], v[190:193], v[16:19]
	v_mfma_f32_16x16x32_bf16 v[8:11], v[138:141], v[212:215], v[8:11]
	v_mfma_f32_16x16x32_bf16 v[0:3], v[150:153], v[212:215], v[0:3]
	v_mfma_f32_16x16x32_bf16 v[56:59], v[142:145], v[178:181], v[56:59]
	v_mfma_f32_16x16x32_bf16 v[48:51], v[154:157], v[178:181], v[48:51]
	v_mfma_f32_16x16x32_bf16 v[40:43], v[142:145], v[186:189], v[40:43]
	v_mfma_f32_16x16x32_bf16 v[32:35], v[154:157], v[186:189], v[32:35]
	v_mfma_f32_16x16x32_bf16 v[24:27], v[142:145], v[194:197], v[24:27]
	v_mfma_f32_16x16x32_bf16 v[16:19], v[154:157], v[194:197], v[16:19]
	v_mfma_f32_16x16x32_bf16 v[8:11], v[142:145], v[216:219], v[8:11]
	v_mfma_f32_16x16x32_bf16 v[0:3], v[154:157], v[216:219], v[0:3]
	s_setprio 0
	s_setprio 1
	v_mfma_f32_16x16x32_bf16 v[60:63], v[158:161], v[174:177], v[60:63]
	v_mfma_f32_16x16x32_bf16 v[52:55], v[166:169], v[174:177], v[52:55]
	v_mfma_f32_16x16x32_bf16 v[44:47], v[158:161], v[182:185], v[44:47]
	v_mfma_f32_16x16x32_bf16 v[36:39], v[166:169], v[182:185], v[36:39]
	v_mfma_f32_16x16x32_bf16 v[28:31], v[158:161], v[190:193], v[28:31]
	v_mfma_f32_16x16x32_bf16 v[20:23], v[166:169], v[190:193], v[20:23]
	v_mfma_f32_16x16x32_bf16 v[12:15], v[158:161], v[212:215], v[12:15]
	v_mfma_f32_16x16x32_bf16 v[4:7], v[166:169], v[212:215], v[4:7]
	v_mfma_f32_16x16x32_bf16 v[60:63], v[162:165], v[178:181], v[60:63]
	v_mfma_f32_16x16x32_bf16 v[52:55], v[170:173], v[178:181], v[52:55]
	v_mfma_f32_16x16x32_bf16 v[44:47], v[162:165], v[186:189], v[44:47]
	v_mfma_f32_16x16x32_bf16 v[36:39], v[170:173], v[186:189], v[36:39]
	v_mfma_f32_16x16x32_bf16 v[28:31], v[162:165], v[194:197], v[28:31]
	v_mfma_f32_16x16x32_bf16 v[20:23], v[170:173], v[194:197], v[20:23]
	v_mfma_f32_16x16x32_bf16 v[12:15], v[162:165], v[216:219], v[12:15]
	v_mfma_f32_16x16x32_bf16 v[4:7], v[170:173], v[216:219], v[4:7]
	s_setprio 0
	s_barrier
	s_add_i32 s61, s61, 2
	s_add_u32 s24, s24, 0x100
	s_addc_u32 s25, s25, 0
	s_add_u32 s35, s35, 0x100
	s_addc_u32 s52, s52, 0

.LBB0_460:
	s_ashr_i32 s17, s16, 31
	s_lshl_b64 s[0:1], s[16:17], 20
	s_add_u32 s18, s26, s0
	s_addc_u32 s19, s27, s1
	s_and_b64 s[0:1], s[6:7], exec
	s_cselect_b32 s17, s19, s31
	s_cselect_b32 s61, s18, s30
	s_ashr_i32 s15, s14, 31
	s_lshl_b64 s[0:1], s[14:15], 20
	s_add_u32 s20, s40, s0
	s_addc_u32 s21, s41, s1
	s_and_b64 s[0:1], s[6:7], exec
	s_cselect_b32 s15, s21, s37
	s_cselect_b32 s34, s20, s36
	s_add_u32 s30, s30, 0x80080
	s_addc_u32 s31, s31, 0
	s_add_u32 s35, s36, 0x100
	s_addc_u32 s69, s37, 0
	s_mov_b32 s79, -2
	s_add_u32 s0, s30, 0xfff80080
	s_addc_u32 s1, s31, -1
	s_add_i32 s59, 0, 0x10000
	s_cmp_eq_u32 s79, 28
	s_cselect_b32 s39, s17, s1
	s_cselect_b32 s38, s61, s0
	s_cselect_b32 s37, s15, s69
	s_cselect_b32 s36, s34, s35
	s_add_i32 s63, 0, 0x14000
	v_add_u32_e32 v154, s59, v147
	v_add_u32_e32 v170, s63, v147
	ds_read_b128 v[138:141], v154
	ds_read_b128 v[142:145], v154 offset:1024
	ds_read_b128 v[150:153], v154 offset:2048
	ds_read_b128 v[154:157], v154 offset:3072
	ds_read_b128 v[158:161], v170
	ds_read_b128 v[162:165], v170 offset:1024
	ds_read_b128 v[166:169], v170 offset:2048
	ds_read_b128 v[170:173], v170 offset:3072
	v_lshl_add_u64 v[220:221], s[30:31], 0, v[134:135]
	s_add_i32 m0, s44, 0xc000
	ds_read_b128 v[174:177], v149
	ds_read_b128 v[178:181], v149 offset:1024
	ds_read_b128 v[182:185], v149 offset:2048
	ds_read_b128 v[186:189], v149 offset:3072
	ds_read_b128 v[190:193], v149 offset:4096
	ds_read_b128 v[194:197], v149 offset:5120
	ds_read_b128 v[212:215], v149 offset:6144
	ds_read_b128 v[216:219], v149 offset:7168
	global_load_lds_dwordx4 v[220:221], off
	v_lshl_add_u64 v[220:221], s[30:31], 0, v[136:137]
	s_add_i32 m0, s44, 0xe000
	s_nop 0
	global_load_lds_dwordx4 v[220:221], off
	s_waitcnt vmcnt(8)
	s_waitcnt lgkmcnt(0)
	s_barrier
	s_setprio 1
	s_waitcnt lgkmcnt(0)
	v_mfma_f32_16x16x32_bf16 v[124:127], v[138:141], v[174:177], 0
	v_mfma_f32_16x16x32_bf16 v[120:123], v[150:153], v[174:177], 0
	v_mfma_f32_16x16x32_bf16 v[108:111], v[138:141], v[182:185], 0
	v_mfma_f32_16x16x32_bf16 v[104:107], v[150:153], v[182:185], 0
	v_mfma_f32_16x16x32_bf16 v[92:95], v[138:141], v[190:193], 0
	v_mfma_f32_16x16x32_bf16 v[88:91], v[150:153], v[190:193], 0
	v_mfma_f32_16x16x32_bf16 v[76:79], v[138:141], v[212:215], 0
	v_mfma_f32_16x16x32_bf16 v[72:75], v[150:153], v[212:215], 0
	v_mfma_f32_16x16x32_bf16 v[124:127], v[142:145], v[178:181], v[124:127]
	v_mfma_f32_16x16x32_bf16 v[120:123], v[154:157], v[178:181], v[120:123]
	v_mfma_f32_16x16x32_bf16 v[108:111], v[142:145], v[186:189], v[108:111]
	v_mfma_f32_16x16x32_bf16 v[104:107], v[154:157], v[186:189], v[104:107]
	v_mfma_f32_16x16x32_bf16 v[92:95], v[142:145], v[194:197], v[92:95]
	v_mfma_f32_16x16x32_bf16 v[88:91], v[154:157], v[194:197], v[88:91]
	v_mfma_f32_16x16x32_bf16 v[76:79], v[142:145], v[216:219], v[76:79]
	v_mfma_f32_16x16x32_bf16 v[72:75], v[154:157], v[216:219], v[72:75]
	s_setprio 0
	s_setprio 1
	v_mfma_f32_16x16x32_bf16 v[116:119], v[158:161], v[174:177], 0
	v_mfma_f32_16x16x32_bf16 v[112:115], v[166:169], v[174:177], 0
	v_mfma_f32_16x16x32_bf16 v[100:103], v[158:161], v[182:185], 0
	v_mfma_f32_16x16x32_bf16 v[96:99], v[166:169], v[182:185], 0
	v_mfma_f32_16x16x32_bf16 v[84:87], v[158:161], v[190:193], 0
	v_mfma_f32_16x16x32_bf16 v[80:83], v[166:169], v[190:193], 0
	v_mfma_f32_16x16x32_bf16 v[68:71], v[158:161], v[212:215], 0
	v_mfma_f32_16x16x32_bf16 v[64:67], v[166:169], v[212:215], 0
	v_mfma_f32_16x16x32_bf16 v[116:119], v[162:165], v[178:181], v[116:119]
	v_mfma_f32_16x16x32_bf16 v[112:115], v[170:173], v[178:181], v[112:115]
	v_mfma_f32_16x16x32_bf16 v[100:103], v[162:165], v[186:189], v[100:103]
	v_mfma_f32_16x16x32_bf16 v[96:99], v[170:173], v[186:189], v[96:99]
	v_mfma_f32_16x16x32_bf16 v[84:87], v[162:165], v[194:197], v[84:87]
	v_mfma_f32_16x16x32_bf16 v[80:83], v[170:173], v[194:197], v[80:83]
	v_mfma_f32_16x16x32_bf16 v[68:71], v[162:165], v[216:219], v[68:71]
	v_mfma_f32_16x16x32_bf16 v[64:67], v[170:173], v[216:219], v[64:67]
	s_setprio 0
	s_barrier
	s_add_i32 s0, s59, s42
	v_lshl_add_u64 v[220:221], s[36:37], 0, v[198:199]
	s_mov_b32 m0, s0
	ds_read_b128 v[174:177], v149 offset:16384
	ds_read_b128 v[178:181], v149 offset:17408
	ds_read_b128 v[182:185], v149 offset:18432
	ds_read_b128 v[186:189], v149 offset:19456
	ds_read_b128 v[190:193], v149 offset:20480
	ds_read_b128 v[194:197], v149 offset:21504
	ds_read_b128 v[212:215], v149 offset:22528
	ds_read_b128 v[216:219], v149 offset:23552
	global_load_lds_dwordx4 v[220:221], off
	s_add_i32 m0, s0, 0x2000
	s_add_u32 s0, s36, 0x80000
	v_lshl_add_u64 v[222:223], s[36:37], 0, v[128:129]
	s_addc_u32 s1, s37, 0
	s_add_i32 s59, s63, s42
	global_load_lds_dwordx4 v[222:223], off
	v_lshl_add_u64 v[224:225], s[0:1], 0, v[198:199]
	s_mov_b32 m0, s59
	v_lshl_add_u64 v[226:227], s[38:39], 0, v[130:131]
	global_load_lds_dwordx4 v[224:225], off
	v_lshl_add_u64 v[224:225], s[0:1], 0, v[128:129]
	s_add_i32 m0, s59, 0x2000
	s_nop 0
	global_load_lds_dwordx4 v[224:225], off
	v_lshl_add_u64 v[224:225], s[38:39], 0, v[132:133]
	s_mov_b32 m0, s44
	s_nop 0
	global_load_lds_dwordx4 v[224:225], off
	s_mov_b32 m0, s45
	s_nop 0
	global_load_lds_dwordx4 v[226:227], off
	s_waitcnt vmcnt(8)
	s_waitcnt lgkmcnt(0)
	s_barrier
	s_setprio 1
	s_waitcnt lgkmcnt(0)
	v_mfma_f32_16x16x32_bf16 v[60:63], v[138:141], v[174:177], 0
	v_mfma_f32_16x16x32_bf16 v[56:59], v[150:153], v[174:177], 0
	v_mfma_f32_16x16x32_bf16 v[44:47], v[138:141], v[182:185], 0
	v_mfma_f32_16x16x32_bf16 v[40:43], v[150:153], v[182:185], 0
	v_mfma_f32_16x16x32_bf16 v[28:31], v[138:141], v[190:193], 0
	v_mfma_f32_16x16x32_bf16 v[24:27], v[150:153], v[190:193], 0
	v_mfma_f32_16x16x32_bf16 v[12:15], v[138:141], v[212:215], 0
	v_mfma_f32_16x16x32_bf16 v[8:11], v[150:153], v[212:215], 0
	v_mfma_f32_16x16x32_bf16 v[60:63], v[142:145], v[178:181], v[60:63]
	v_mfma_f32_16x16x32_bf16 v[56:59], v[154:157], v[178:181], v[56:59]
	v_mfma_f32_16x16x32_bf16 v[44:47], v[142:145], v[186:189], v[44:47]
	v_mfma_f32_16x16x32_bf16 v[40:43], v[154:157], v[186:189], v[40:43]
	v_mfma_f32_16x16x32_bf16 v[28:31], v[142:145], v[194:197], v[28:31]
	v_mfma_f32_16x16x32_bf16 v[24:27], v[154:157], v[194:197], v[24:27]
	v_mfma_f32_16x16x32_bf16 v[12:15], v[142:145], v[216:219], v[12:15]
	v_mfma_f32_16x16x32_bf16 v[8:11], v[154:157], v[216:219], v[8:11]
	s_setprio 0
	s_setprio 1
	v_mfma_f32_16x16x32_bf16 v[52:55], v[158:161], v[174:177], 0
	v_mfma_f32_16x16x32_bf16 v[48:51], v[166:169], v[174:177], 0
	v_mfma_f32_16x16x32_bf16 v[36:39], v[158:161], v[182:185], 0
	v_mfma_f32_16x16x32_bf16 v[32:35], v[166:169], v[182:185], 0
	v_mfma_f32_16x16x32_bf16 v[20:23], v[158:161], v[190:193], 0
	v_mfma_f32_16x16x32_bf16 v[16:19], v[166:169], v[190:193], 0
	v_mfma_f32_16x16x32_bf16 v[4:7], v[158:161], v[212:215], 0
	v_mfma_f32_16x16x32_bf16 v[0:3], v[166:169], v[212:215], 0
	v_mfma_f32_16x16x32_bf16 v[52:55], v[162:165], v[178:181], v[52:55]
	v_mfma_f32_16x16x32_bf16 v[48:51], v[170:173], v[178:181], v[48:51]
	v_mfma_f32_16x16x32_bf16 v[36:39], v[162:165], v[186:189], v[36:39]
	v_mfma_f32_16x16x32_bf16 v[32:35], v[170:173], v[186:189], v[32:35]
	v_mfma_f32_16x16x32_bf16 v[20:23], v[162:165], v[194:197], v[20:23]
	v_mfma_f32_16x16x32_bf16 v[16:19], v[170:173], v[194:197], v[16:19]
	v_mfma_f32_16x16x32_bf16 v[4:7], v[162:165], v[216:219], v[4:7]
	v_mfma_f32_16x16x32_bf16 v[0:3], v[170:173], v[216:219], v[0:3]
	s_setprio 0
	s_barrier
	s_add_i32 s59, 0, 0x18000
	s_add_i32 s63, 0, 0x1c000
	v_add_u32_e32 v154, s59, v147
	v_add_u32_e32 v170, s63, v147
	ds_read_b128 v[138:141], v154
	ds_read_b128 v[142:145], v154 offset:1024
	ds_read_b128 v[150:153], v154 offset:2048
	ds_read_b128 v[154:157], v154 offset:3072
	ds_read_b128 v[158:161], v170
	ds_read_b128 v[162:165], v170 offset:1024
	ds_read_b128 v[166:169], v170 offset:2048
	ds_read_b128 v[170:173], v170 offset:3072
	s_add_u32 s0, s38, 0x80000
	s_addc_u32 s1, s39, 0
	s_mov_b32 m0, s46
	v_lshl_add_u64 v[228:229], s[0:1], 0, v[132:133]
	ds_read_b128 v[174:177], v149 offset:32768
	ds_read_b128 v[178:181], v149 offset:33792
	ds_read_b128 v[182:185], v149 offset:34816
	ds_read_b128 v[186:189], v149 offset:35840
	ds_read_b128 v[190:193], v149 offset:36864
	ds_read_b128 v[194:197], v149 offset:37888
	ds_read_b128 v[212:215], v149 offset:38912
	ds_read_b128 v[216:219], v149 offset:39936
	global_load_lds_dwordx4 v[228:229], off
	v_lshl_add_u64 v[228:229], s[0:1], 0, v[130:131]
	s_mov_b32 m0, s47
	s_nop 0
	global_load_lds_dwordx4 v[228:229], off
	s_waitcnt vmcnt(8)
	s_waitcnt lgkmcnt(0)
	s_barrier
	s_setprio 1
	s_waitcnt lgkmcnt(0)
	v_mfma_f32_16x16x32_bf16 v[124:127], v[138:141], v[174:177], v[124:127]
	v_mfma_f32_16x16x32_bf16 v[120:123], v[150:153], v[174:177], v[120:123]
	v_mfma_f32_16x16x32_bf16 v[108:111], v[138:141], v[182:185], v[108:111]
	v_mfma_f32_16x16x32_bf16 v[104:107], v[150:153], v[182:185], v[104:107]
	v_mfma_f32_16x16x32_bf16 v[92:95], v[138:141], v[190:193], v[92:95]
	v_mfma_f32_16x16x32_bf16 v[88:91], v[150:153], v[190:193], v[88:91]
	v_mfma_f32_16x16x32_bf16 v[76:79], v[138:141], v[212:215], v[76:79]
	v_mfma_f32_16x16x32_bf16 v[72:75], v[150:153], v[212:215], v[72:75]
	v_mfma_f32_16x16x32_bf16 v[124:127], v[142:145], v[178:181], v[124:127]
	v_mfma_f32_16x16x32_bf16 v[120:123], v[154:157], v[178:181], v[120:123]
	v_mfma_f32_16x16x32_bf16 v[108:111], v[142:145], v[186:189], v[108:111]
	v_mfma_f32_16x16x32_bf16 v[104:107], v[154:157], v[186:189], v[104:107]
	v_mfma_f32_16x16x32_bf16 v[92:95], v[142:145], v[194:197], v[92:95]
	v_mfma_f32_16x16x32_bf16 v[88:91], v[154:157], v[194:197], v[88:91]
	v_mfma_f32_16x16x32_bf16 v[76:79], v[142:145], v[216:219], v[76:79]
	v_mfma_f32_16x16x32_bf16 v[72:75], v[154:157], v[216:219], v[72:75]
	s_setprio 0
	s_setprio 1
	v_mfma_f32_16x16x32_bf16 v[116:119], v[158:161], v[174:177], v[116:119]
	v_mfma_f32_16x16x32_bf16 v[112:115], v[166:169], v[174:177], v[112:115]
	v_mfma_f32_16x16x32_bf16 v[100:103], v[158:161], v[182:185], v[100:103]
	v_mfma_f32_16x16x32_bf16 v[96:99], v[166:169], v[182:185], v[96:99]
	v_mfma_f32_16x16x32_bf16 v[84:87], v[158:161], v[190:193], v[84:87]
	v_mfma_f32_16x16x32_bf16 v[80:83], v[166:169], v[190:193], v[80:83]
	v_mfma_f32_16x16x32_bf16 v[68:71], v[158:161], v[212:215], v[68:71]
	v_mfma_f32_16x16x32_bf16 v[64:67], v[166:169], v[212:215], v[64:67]
	v_mfma_f32_16x16x32_bf16 v[116:119], v[162:165], v[178:181], v[116:119]
	v_mfma_f32_16x16x32_bf16 v[112:115], v[170:173], v[178:181], v[112:115]
	v_mfma_f32_16x16x32_bf16 v[100:103], v[162:165], v[186:189], v[100:103]
	v_mfma_f32_16x16x32_bf16 v[96:99], v[170:173], v[186:189], v[96:99]
	v_mfma_f32_16x16x32_bf16 v[84:87], v[162:165], v[194:197], v[84:87]
	v_mfma_f32_16x16x32_bf16 v[80:83], v[170:173], v[194:197], v[80:83]
	v_mfma_f32_16x16x32_bf16 v[68:71], v[162:165], v[216:219], v[68:71]
	v_mfma_f32_16x16x32_bf16 v[64:67], v[170:173], v[216:219], v[64:67]
	s_setprio 0
	s_barrier
	s_add_i32 s0, s59, s42
	v_lshl_add_u64 v[220:221], v[220:221], 0, s[54:55]
	s_mov_b32 m0, s0
	ds_read_b128 v[174:177], v149 offset:49152
	ds_read_b128 v[178:181], v149 offset:50176
	ds_read_b128 v[182:185], v149 offset:51200
	ds_read_b128 v[186:189], v149 offset:52224
	ds_read_b128 v[190:193], v149 offset:53248
	ds_read_b128 v[194:197], v149 offset:54272
	ds_read_b128 v[212:215], v149 offset:55296
	ds_read_b128 v[216:219], v149 offset:56320
	global_load_lds_dwordx4 v[220:221], off
	s_add_i32 m0, s0, 0x2000
	s_add_u32 s0, s36, 0x80080
	v_lshl_add_u64 v[220:221], v[222:223], 0, s[54:55]
	s_addc_u32 s1, s37, 0
	s_add_i32 s36, s63, s42
	global_load_lds_dwordx4 v[220:221], off
	v_lshl_add_u64 v[220:221], s[0:1], 0, v[198:199]
	s_mov_b32 m0, s36
	s_nop 0
	global_load_lds_dwordx4 v[220:221], off
	v_lshl_add_u64 v[220:221], s[0:1], 0, v[128:129]
	s_add_i32 m0, s36, 0x2000
	s_nop 0
	global_load_lds_dwordx4 v[220:221], off
	v_lshl_add_u64 v[220:221], v[224:225], 0, s[54:55]
	s_mov_b32 m0, s49
	s_nop 0
	global_load_lds_dwordx4 v[220:221], off
	v_lshl_add_u64 v[220:221], v[226:227], 0, s[54:55]
	s_mov_b32 m0, s50
	s_nop 0
	global_load_lds_dwordx4 v[220:221], off
	s_waitcnt vmcnt(8)
	s_waitcnt lgkmcnt(0)
	s_barrier
	s_setprio 1
	s_waitcnt lgkmcnt(0)
	v_mfma_f32_16x16x32_bf16 v[60:63], v[138:141], v[174:177], v[60:63]
	v_mfma_f32_16x16x32_bf16 v[56:59], v[150:153], v[174:177], v[56:59]
	v_mfma_f32_16x16x32_bf16 v[44:47], v[138:141], v[182:185], v[44:47]
	v_mfma_f32_16x16x32_bf16 v[40:43], v[150:153], v[182:185], v[40:43]
	v_mfma_f32_16x16x32_bf16 v[28:31], v[138:141], v[190:193], v[28:31]
	v_mfma_f32_16x16x32_bf16 v[24:27], v[150:153], v[190:193], v[24:27]
	v_mfma_f32_16x16x32_bf16 v[12:15], v[138:141], v[212:215], v[12:15]
	v_mfma_f32_16x16x32_bf16 v[8:11], v[150:153], v[212:215], v[8:11]
	v_mfma_f32_16x16x32_bf16 v[60:63], v[142:145], v[178:181], v[60:63]
	v_mfma_f32_16x16x32_bf16 v[56:59], v[154:157], v[178:181], v[56:59]
	v_mfma_f32_16x16x32_bf16 v[44:47], v[142:145], v[186:189], v[44:47]
	v_mfma_f32_16x16x32_bf16 v[40:43], v[154:157], v[186:189], v[40:43]
	v_mfma_f32_16x16x32_bf16 v[28:31], v[142:145], v[194:197], v[28:31]
	v_mfma_f32_16x16x32_bf16 v[24:27], v[154:157], v[194:197], v[24:27]
	v_mfma_f32_16x16x32_bf16 v[12:15], v[142:145], v[216:219], v[12:15]
	v_mfma_f32_16x16x32_bf16 v[8:11], v[154:157], v[216:219], v[8:11]
	s_setprio 0
	s_setprio 1
	v_mfma_f32_16x16x32_bf16 v[52:55], v[158:161], v[174:177], v[52:55]
	v_mfma_f32_16x16x32_bf16 v[48:51], v[166:169], v[174:177], v[48:51]
	v_mfma_f32_16x16x32_bf16 v[36:39], v[158:161], v[182:185], v[36:39]
	v_mfma_f32_16x16x32_bf16 v[32:35], v[166:169], v[182:185], v[32:35]
	v_mfma_f32_16x16x32_bf16 v[20:23], v[158:161], v[190:193], v[20:23]
	v_mfma_f32_16x16x32_bf16 v[16:19], v[166:169], v[190:193], v[16:19]
	v_mfma_f32_16x16x32_bf16 v[4:7], v[158:161], v[212:215], v[4:7]
	v_mfma_f32_16x16x32_bf16 v[0:3], v[166:169], v[212:215], v[0:3]
	v_mfma_f32_16x16x32_bf16 v[52:55], v[162:165], v[178:181], v[52:55]
	v_mfma_f32_16x16x32_bf16 v[48:51], v[170:173], v[178:181], v[48:51]
	v_mfma_f32_16x16x32_bf16 v[36:39], v[162:165], v[186:189], v[36:39]
	v_mfma_f32_16x16x32_bf16 v[32:35], v[170:173], v[186:189], v[32:35]
	v_mfma_f32_16x16x32_bf16 v[20:23], v[162:165], v[194:197], v[20:23]
	v_mfma_f32_16x16x32_bf16 v[16:19], v[170:173], v[194:197], v[16:19]
	v_mfma_f32_16x16x32_bf16 v[4:7], v[162:165], v[216:219], v[4:7]
	v_mfma_f32_16x16x32_bf16 v[0:3], v[170:173], v[216:219], v[0:3]
	s_setprio 0
	s_barrier
	s_add_i32 s79, s79, 2
	s_add_u32 s30, s30, 0x100
	s_addc_u32 s31, s31, 0
	s_add_u32 s35, s35, 0x100
	s_addc_u32 s69, s69, 0

.LBB0_492:
	s_add_u32 s34, s30, 0x100
	s_addc_u32 s35, s31, 0
	s_mov_b32 s81, -2
	s_waitcnt lgkmcnt(0)
	s_add_u32 s30, s28, 0x100
	s_addc_u32 s31, s29, 0
	s_add_i32 s0, 0, 0x10000
	s_cmpk_eq_i32 s81, 0x54
	s_cselect_b32 s39, s11, s31
	s_cselect_b32 s38, s10, s30
	s_cselect_b32 s37, s21, s35
	s_cselect_b32 s36, s20, s34
	s_add_i32 s59, 0, 0x14000
	v_add_u32_e32 v140, s0, v195
	v_add_u32_e32 v156, s59, v195
	ds_read_b128 v[120:123], v140
	ds_read_b128 v[124:127], v140 offset:1024
	ds_read_b128 v[128:131], v140 offset:2048
	ds_read_b128 v[140:143], v140 offset:3072
	ds_read_b128 v[144:147], v156
	ds_read_b128 v[148:151], v156 offset:1024
	ds_read_b128 v[152:155], v156 offset:2048
	ds_read_b128 v[156:159], v156 offset:3072
	v_lshl_add_u64 v[216:217], s[28:29], 0, v[178:179]
	s_add_i32 m0, s45, 0xc000
	ds_read_b128 v[160:163], v197
	ds_read_b128 v[164:167], v197 offset:1024
	ds_read_b128 v[168:171], v197 offset:2048
	ds_read_b128 v[172:175], v197 offset:3072
	ds_read_b128 v[182:185], v197 offset:4096
	ds_read_b128 v[186:189], v197 offset:5120
	ds_read_b128 v[190:193], v197 offset:6144
	ds_read_b128 v[212:215], v197 offset:7168
	global_load_lds_dwordx4 v[216:217], off
	v_lshl_add_u64 v[216:217], s[28:29], 0, v[180:181]
	s_add_i32 m0, s45, 0xe000
	s_nop 0
	global_load_lds_dwordx4 v[216:217], off
	s_waitcnt vmcnt(8)
	s_waitcnt lgkmcnt(0)
	s_barrier
	s_setprio 1
	s_waitcnt lgkmcnt(0)
	v_mfma_f32_16x16x32_bf16 v[136:139], v[120:123], v[160:163], 0
	v_mfma_f32_16x16x32_bf16 v[132:135], v[128:131], v[160:163], 0
	v_mfma_f32_16x16x32_bf16 v[108:111], v[120:123], v[168:171], 0
	v_mfma_f32_16x16x32_bf16 v[104:107], v[128:131], v[168:171], 0
	v_mfma_f32_16x16x32_bf16 v[92:95], v[120:123], v[182:185], 0
	v_mfma_f32_16x16x32_bf16 v[88:91], v[128:131], v[182:185], 0
	v_mfma_f32_16x16x32_bf16 v[76:79], v[120:123], v[190:193], 0
	v_mfma_f32_16x16x32_bf16 v[72:75], v[128:131], v[190:193], 0
	v_mfma_f32_16x16x32_bf16 v[136:139], v[124:127], v[164:167], v[136:139]
	v_mfma_f32_16x16x32_bf16 v[132:135], v[140:143], v[164:167], v[132:135]
	v_mfma_f32_16x16x32_bf16 v[108:111], v[124:127], v[172:175], v[108:111]
	v_mfma_f32_16x16x32_bf16 v[104:107], v[140:143], v[172:175], v[104:107]
	v_mfma_f32_16x16x32_bf16 v[92:95], v[124:127], v[186:189], v[92:95]
	v_mfma_f32_16x16x32_bf16 v[88:91], v[140:143], v[186:189], v[88:91]
	v_mfma_f32_16x16x32_bf16 v[76:79], v[124:127], v[212:215], v[76:79]
	v_mfma_f32_16x16x32_bf16 v[72:75], v[140:143], v[212:215], v[72:75]
	s_setprio 0
	s_setprio 1
	v_mfma_f32_16x16x32_bf16 v[116:119], v[144:147], v[160:163], 0
	v_mfma_f32_16x16x32_bf16 v[112:115], v[152:155], v[160:163], 0
	v_mfma_f32_16x16x32_bf16 v[100:103], v[144:147], v[168:171], 0
	v_mfma_f32_16x16x32_bf16 v[96:99], v[152:155], v[168:171], 0
	v_mfma_f32_16x16x32_bf16 v[84:87], v[144:147], v[182:185], 0
	v_mfma_f32_16x16x32_bf16 v[80:83], v[152:155], v[182:185], 0
	v_mfma_f32_16x16x32_bf16 v[68:71], v[144:147], v[190:193], 0
	v_mfma_f32_16x16x32_bf16 v[64:67], v[152:155], v[190:193], 0
	v_mfma_f32_16x16x32_bf16 v[116:119], v[148:151], v[164:167], v[116:119]
	v_mfma_f32_16x16x32_bf16 v[112:115], v[156:159], v[164:167], v[112:115]
	v_mfma_f32_16x16x32_bf16 v[100:103], v[148:151], v[172:175], v[100:103]
	v_mfma_f32_16x16x32_bf16 v[96:99], v[156:159], v[172:175], v[96:99]
	v_mfma_f32_16x16x32_bf16 v[84:87], v[148:151], v[186:189], v[84:87]
	v_mfma_f32_16x16x32_bf16 v[80:83], v[156:159], v[186:189], v[80:83]
	v_mfma_f32_16x16x32_bf16 v[68:71], v[148:151], v[212:215], v[68:71]
	v_mfma_f32_16x16x32_bf16 v[64:67], v[156:159], v[212:215], v[64:67]
	s_setprio 0
	s_barrier
	s_add_i32 s0, s0, s44
	v_lshl_add_u64 v[216:217], s[36:37], 0, v[198:199]
	s_mov_b32 m0, s0
	ds_read_b128 v[160:163], v197 offset:16384
	ds_read_b128 v[164:167], v197 offset:17408
	ds_read_b128 v[168:171], v197 offset:18432
	ds_read_b128 v[172:175], v197 offset:19456
	ds_read_b128 v[182:185], v197 offset:20480
	ds_read_b128 v[186:189], v197 offset:21504
	ds_read_b128 v[190:193], v197 offset:22528
	ds_read_b128 v[212:215], v197 offset:23552
	global_load_lds_dwordx4 v[216:217], off
	s_add_i32 m0, s0, 0x2000
	s_add_u32 s0, s36, 0x160000
	v_lshl_add_u64 v[218:219], s[36:37], 0, v[176:177]
	s_addc_u32 s1, s37, 0
	s_add_i32 s28, s59, s44
	global_load_lds_dwordx4 v[218:219], off
	v_lshl_add_u64 v[220:221], s[0:1], 0, v[198:199]
	s_mov_b32 m0, s28
	v_lshl_add_u64 v[222:223], s[38:39], 0, v[176:177]
	global_load_lds_dwordx4 v[220:221], off
	v_lshl_add_u64 v[220:221], s[0:1], 0, v[176:177]
	s_add_i32 m0, s28, 0x2000
	s_nop 0
	global_load_lds_dwordx4 v[220:221], off
	v_lshl_add_u64 v[220:221], s[38:39], 0, v[198:199]
	s_mov_b32 m0, s45
	s_nop 0
	global_load_lds_dwordx4 v[220:221], off
	s_mov_b32 m0, s46
	s_nop 0
	global_load_lds_dwordx4 v[222:223], off
	s_waitcnt vmcnt(8)
	s_waitcnt lgkmcnt(0)
	s_barrier
	s_setprio 1
	s_waitcnt lgkmcnt(0)
	v_mfma_f32_16x16x32_bf16 v[60:63], v[120:123], v[160:163], 0
	v_mfma_f32_16x16x32_bf16 v[56:59], v[128:131], v[160:163], 0
	v_mfma_f32_16x16x32_bf16 v[44:47], v[120:123], v[168:171], 0
	v_mfma_f32_16x16x32_bf16 v[40:43], v[128:131], v[168:171], 0
	v_mfma_f32_16x16x32_bf16 v[28:31], v[120:123], v[182:185], 0
	v_mfma_f32_16x16x32_bf16 v[24:27], v[128:131], v[182:185], 0
	v_mfma_f32_16x16x32_bf16 v[12:15], v[120:123], v[190:193], 0
	v_mfma_f32_16x16x32_bf16 v[8:11], v[128:131], v[190:193], 0
	v_mfma_f32_16x16x32_bf16 v[60:63], v[124:127], v[164:167], v[60:63]
	v_mfma_f32_16x16x32_bf16 v[56:59], v[140:143], v[164:167], v[56:59]
	v_mfma_f32_16x16x32_bf16 v[44:47], v[124:127], v[172:175], v[44:47]
	v_mfma_f32_16x16x32_bf16 v[40:43], v[140:143], v[172:175], v[40:43]
	v_mfma_f32_16x16x32_bf16 v[28:31], v[124:127], v[186:189], v[28:31]
	v_mfma_f32_16x16x32_bf16 v[24:27], v[140:143], v[186:189], v[24:27]
	v_mfma_f32_16x16x32_bf16 v[12:15], v[124:127], v[212:215], v[12:15]
	v_mfma_f32_16x16x32_bf16 v[8:11], v[140:143], v[212:215], v[8:11]
	s_setprio 0
	s_setprio 1
	v_mfma_f32_16x16x32_bf16 v[52:55], v[144:147], v[160:163], 0
	v_mfma_f32_16x16x32_bf16 v[48:51], v[152:155], v[160:163], 0
	v_mfma_f32_16x16x32_bf16 v[36:39], v[144:147], v[168:171], 0
	v_mfma_f32_16x16x32_bf16 v[32:35], v[152:155], v[168:171], 0
	v_mfma_f32_16x16x32_bf16 v[20:23], v[144:147], v[182:185], 0
	v_mfma_f32_16x16x32_bf16 v[16:19], v[152:155], v[182:185], 0
	v_mfma_f32_16x16x32_bf16 v[4:7], v[144:147], v[190:193], 0
	v_mfma_f32_16x16x32_bf16 v[0:3], v[152:155], v[190:193], 0
	v_mfma_f32_16x16x32_bf16 v[52:55], v[148:151], v[164:167], v[52:55]
	v_mfma_f32_16x16x32_bf16 v[48:51], v[156:159], v[164:167], v[48:51]
	v_mfma_f32_16x16x32_bf16 v[36:39], v[148:151], v[172:175], v[36:39]
	v_mfma_f32_16x16x32_bf16 v[32:35], v[156:159], v[172:175], v[32:35]
	v_mfma_f32_16x16x32_bf16 v[20:23], v[148:151], v[186:189], v[20:23]
	v_mfma_f32_16x16x32_bf16 v[16:19], v[156:159], v[186:189], v[16:19]
	v_mfma_f32_16x16x32_bf16 v[4:7], v[148:151], v[212:215], v[4:7]
	v_mfma_f32_16x16x32_bf16 v[0:3], v[156:159], v[212:215], v[0:3]
	s_setprio 0
	s_barrier
	s_add_i32 s28, 0, 0x18000
	s_add_i32 s29, 0, 0x1c000
	v_add_u32_e32 v140, s28, v195
	v_add_u32_e32 v156, s29, v195
	ds_read_b128 v[120:123], v140
	ds_read_b128 v[124:127], v140 offset:1024
	ds_read_b128 v[128:131], v140 offset:2048
	ds_read_b128 v[140:143], v140 offset:3072
	ds_read_b128 v[144:147], v156
	ds_read_b128 v[148:151], v156 offset:1024
	ds_read_b128 v[152:155], v156 offset:2048
	ds_read_b128 v[156:159], v156 offset:3072
	s_add_u32 s0, s38, 0x160000
	s_addc_u32 s1, s39, 0
	s_mov_b32 m0, s47
	v_lshl_add_u64 v[224:225], s[0:1], 0, v[198:199]
	ds_read_b128 v[160:163], v197 offset:32768
	ds_read_b128 v[164:167], v197 offset:33792
	ds_read_b128 v[168:171], v197 offset:34816
	ds_read_b128 v[172:175], v197 offset:35840
	ds_read_b128 v[182:185], v197 offset:36864
	ds_read_b128 v[186:189], v197 offset:37888
	ds_read_b128 v[190:193], v197 offset:38912
	ds_read_b128 v[212:215], v197 offset:39936
	global_load_lds_dwordx4 v[224:225], off
	v_lshl_add_u64 v[224:225], s[0:1], 0, v[176:177]
	s_mov_b32 m0, s48
	s_nop 0
	global_load_lds_dwordx4 v[224:225], off
	s_waitcnt vmcnt(8)
	s_waitcnt lgkmcnt(0)
	s_barrier
	s_setprio 1
	s_waitcnt lgkmcnt(0)
	v_mfma_f32_16x16x32_bf16 v[136:139], v[120:123], v[160:163], v[136:139]
	v_mfma_f32_16x16x32_bf16 v[132:135], v[128:131], v[160:163], v[132:135]
	v_mfma_f32_16x16x32_bf16 v[108:111], v[120:123], v[168:171], v[108:111]
	v_mfma_f32_16x16x32_bf16 v[104:107], v[128:131], v[168:171], v[104:107]
	v_mfma_f32_16x16x32_bf16 v[92:95], v[120:123], v[182:185], v[92:95]
	v_mfma_f32_16x16x32_bf16 v[88:91], v[128:131], v[182:185], v[88:91]
	v_mfma_f32_16x16x32_bf16 v[76:79], v[120:123], v[190:193], v[76:79]
	v_mfma_f32_16x16x32_bf16 v[72:75], v[128:131], v[190:193], v[72:75]
	v_mfma_f32_16x16x32_bf16 v[136:139], v[124:127], v[164:167], v[136:139]
	v_mfma_f32_16x16x32_bf16 v[132:135], v[140:143], v[164:167], v[132:135]
	v_mfma_f32_16x16x32_bf16 v[108:111], v[124:127], v[172:175], v[108:111]
	v_mfma_f32_16x16x32_bf16 v[104:107], v[140:143], v[172:175], v[104:107]
	v_mfma_f32_16x16x32_bf16 v[92:95], v[124:127], v[186:189], v[92:95]
	v_mfma_f32_16x16x32_bf16 v[88:91], v[140:143], v[186:189], v[88:91]
	v_mfma_f32_16x16x32_bf16 v[76:79], v[124:127], v[212:215], v[76:79]
	v_mfma_f32_16x16x32_bf16 v[72:75], v[140:143], v[212:215], v[72:75]
	s_setprio 0
	s_setprio 1
	v_mfma_f32_16x16x32_bf16 v[116:119], v[144:147], v[160:163], v[116:119]
	v_mfma_f32_16x16x32_bf16 v[112:115], v[152:155], v[160:163], v[112:115]
	v_mfma_f32_16x16x32_bf16 v[100:103], v[144:147], v[168:171], v[100:103]
	v_mfma_f32_16x16x32_bf16 v[96:99], v[152:155], v[168:171], v[96:99]
	v_mfma_f32_16x16x32_bf16 v[84:87], v[144:147], v[182:185], v[84:87]
	v_mfma_f32_16x16x32_bf16 v[80:83], v[152:155], v[182:185], v[80:83]
	v_mfma_f32_16x16x32_bf16 v[68:71], v[144:147], v[190:193], v[68:71]
	v_mfma_f32_16x16x32_bf16 v[64:67], v[152:155], v[190:193], v[64:67]
	v_mfma_f32_16x16x32_bf16 v[116:119], v[148:151], v[164:167], v[116:119]
	v_mfma_f32_16x16x32_bf16 v[112:115], v[156:159], v[164:167], v[112:115]
	v_mfma_f32_16x16x32_bf16 v[100:103], v[148:151], v[172:175], v[100:103]
	v_mfma_f32_16x16x32_bf16 v[96:99], v[156:159], v[172:175], v[96:99]
	v_mfma_f32_16x16x32_bf16 v[84:87], v[148:151], v[186:189], v[84:87]
	v_mfma_f32_16x16x32_bf16 v[80:83], v[156:159], v[186:189], v[80:83]
	v_mfma_f32_16x16x32_bf16 v[68:71], v[148:151], v[212:215], v[68:71]
	v_mfma_f32_16x16x32_bf16 v[64:67], v[156:159], v[212:215], v[64:67]
	s_setprio 0
	s_barrier
	s_add_i32 s0, s28, s44
	v_lshl_add_u64 v[216:217], v[216:217], 0, s[54:55]
	s_mov_b32 m0, s0
	ds_read_b128 v[160:163], v197 offset:49152
	ds_read_b128 v[164:167], v197 offset:50176
	ds_read_b128 v[168:171], v197 offset:51200
	ds_read_b128 v[172:175], v197 offset:52224
	ds_read_b128 v[182:185], v197 offset:53248
	ds_read_b128 v[186:189], v197 offset:54272
	ds_read_b128 v[190:193], v197 offset:55296
	ds_read_b128 v[212:215], v197 offset:56320
	global_load_lds_dwordx4 v[216:217], off
	s_add_i32 m0, s0, 0x2000
	s_add_u32 s0, s36, 0x160080
	v_lshl_add_u64 v[216:217], v[218:219], 0, s[54:55]
	s_addc_u32 s1, s37, 0
	s_add_i32 s28, s29, s44
	global_load_lds_dwordx4 v[216:217], off
	v_lshl_add_u64 v[216:217], s[0:1], 0, v[198:199]
	s_mov_b32 m0, s28
	s_nop 0
	global_load_lds_dwordx4 v[216:217], off
	v_lshl_add_u64 v[216:217], s[0:1], 0, v[176:177]
	s_add_i32 m0, s28, 0x2000
	s_nop 0
	global_load_lds_dwordx4 v[216:217], off
	v_lshl_add_u64 v[216:217], v[220:221], 0, s[54:55]
	s_mov_b32 m0, s49
	s_nop 0
	global_load_lds_dwordx4 v[216:217], off
	v_lshl_add_u64 v[216:217], v[222:223], 0, s[54:55]
	s_mov_b32 m0, s50
	s_nop 0
	global_load_lds_dwordx4 v[216:217], off
	s_waitcnt vmcnt(8)
	s_waitcnt lgkmcnt(0)
	s_barrier
	s_setprio 1
	s_waitcnt lgkmcnt(0)
	v_mfma_f32_16x16x32_bf16 v[60:63], v[120:123], v[160:163], v[60:63]
	v_mfma_f32_16x16x32_bf16 v[56:59], v[128:131], v[160:163], v[56:59]
	v_mfma_f32_16x16x32_bf16 v[44:47], v[120:123], v[168:171], v[44:47]
	v_mfma_f32_16x16x32_bf16 v[40:43], v[128:131], v[168:171], v[40:43]
	v_mfma_f32_16x16x32_bf16 v[28:31], v[120:123], v[182:185], v[28:31]
	v_mfma_f32_16x16x32_bf16 v[24:27], v[128:131], v[182:185], v[24:27]
	v_mfma_f32_16x16x32_bf16 v[12:15], v[120:123], v[190:193], v[12:15]
	v_mfma_f32_16x16x32_bf16 v[8:11], v[128:131], v[190:193], v[8:11]
	v_mfma_f32_16x16x32_bf16 v[60:63], v[124:127], v[164:167], v[60:63]
	v_mfma_f32_16x16x32_bf16 v[56:59], v[140:143], v[164:167], v[56:59]
	v_mfma_f32_16x16x32_bf16 v[44:47], v[124:127], v[172:175], v[44:47]
	v_mfma_f32_16x16x32_bf16 v[40:43], v[140:143], v[172:175], v[40:43]
	v_mfma_f32_16x16x32_bf16 v[28:31], v[124:127], v[186:189], v[28:31]
	v_mfma_f32_16x16x32_bf16 v[24:27], v[140:143], v[186:189], v[24:27]
	v_mfma_f32_16x16x32_bf16 v[12:15], v[124:127], v[212:215], v[12:15]
	v_mfma_f32_16x16x32_bf16 v[8:11], v[140:143], v[212:215], v[8:11]
	s_setprio 0
	s_setprio 1
	v_mfma_f32_16x16x32_bf16 v[52:55], v[144:147], v[160:163], v[52:55]
	v_mfma_f32_16x16x32_bf16 v[48:51], v[152:155], v[160:163], v[48:51]
	v_mfma_f32_16x16x32_bf16 v[36:39], v[144:147], v[168:171], v[36:39]
	v_mfma_f32_16x16x32_bf16 v[32:35], v[152:155], v[168:171], v[32:35]
	v_mfma_f32_16x16x32_bf16 v[20:23], v[144:147], v[182:185], v[20:23]
	v_mfma_f32_16x16x32_bf16 v[16:19], v[152:155], v[182:185], v[16:19]
	v_mfma_f32_16x16x32_bf16 v[4:7], v[144:147], v[190:193], v[4:7]
	v_mfma_f32_16x16x32_bf16 v[0:3], v[152:155], v[190:193], v[0:3]
	v_mfma_f32_16x16x32_bf16 v[52:55], v[148:151], v[164:167], v[52:55]
	v_mfma_f32_16x16x32_bf16 v[48:51], v[156:159], v[164:167], v[48:51]
	v_mfma_f32_16x16x32_bf16 v[36:39], v[148:151], v[172:175], v[36:39]
	v_mfma_f32_16x16x32_bf16 v[32:35], v[156:159], v[172:175], v[32:35]
	v_mfma_f32_16x16x32_bf16 v[20:23], v[148:151], v[186:189], v[20:23]
	v_mfma_f32_16x16x32_bf16 v[16:19], v[156:159], v[186:189], v[16:19]
	v_mfma_f32_16x16x32_bf16 v[4:7], v[148:151], v[212:215], v[4:7]
	v_mfma_f32_16x16x32_bf16 v[0:3], v[156:159], v[212:215], v[0:3]
	s_setprio 0
	s_barrier
	s_add_i32 s81, s81, 2
	s_add_u32 s34, s34, 0x100
	s_addc_u32 s35, s35, 0
	s_mov_b64 s[28:29], s[30:31]

.LBB0_527:
	s_ashr_i32 s17, s16, 31
	s_lshl_b64 s[0:1], s[16:17], 20
	s_add_u32 s18, s26, s0
	s_addc_u32 s19, s27, s1
	s_and_b64 s[0:1], s[6:7], exec
	s_cselect_b32 s17, s19, s31
	s_cselect_b32 s51, s18, s30
	s_ashr_i32 s15, s14, 31
	s_lshl_b64 s[0:1], s[14:15], 20
	s_add_u32 s20, s70, s0
	s_addc_u32 s21, s71, s1
	s_and_b64 s[0:1], s[6:7], exec
	s_cselect_b32 s15, s21, s37
	s_cselect_b32 s34, s20, s36
	s_add_u32 s30, s30, 0x80080
	s_addc_u32 s31, s31, 0
	s_add_u32 s35, s36, 0x100
	s_addc_u32 s52, s37, 0
	s_mov_b32 s61, -2
	s_add_u32 s0, s30, 0xfff80080
	s_addc_u32 s1, s31, -1
	s_add_i32 s59, 0, 0x10000
	s_cmp_eq_u32 s61, 28
	s_cselect_b32 s39, s17, s1
	s_cselect_b32 s38, s51, s0
	s_cselect_b32 s37, s15, s52
	s_cselect_b32 s36, s34, s35
	s_add_i32 s63, 0, 0x14000
	v_add_u32_e32 v154, s59, v147
	v_add_u32_e32 v170, s63, v147
	ds_read_b128 v[138:141], v154
	ds_read_b128 v[142:145], v154 offset:1024
	ds_read_b128 v[150:153], v154 offset:2048
	ds_read_b128 v[154:157], v154 offset:3072
	ds_read_b128 v[158:161], v170
	ds_read_b128 v[162:165], v170 offset:1024
	ds_read_b128 v[166:169], v170 offset:2048
	ds_read_b128 v[170:173], v170 offset:3072
	v_lshl_add_u64 v[220:221], s[30:31], 0, v[134:135]
	s_add_i32 m0, s42, 0xc000
	ds_read_b128 v[174:177], v149
	ds_read_b128 v[178:181], v149 offset:1024
	ds_read_b128 v[182:185], v149 offset:2048
	ds_read_b128 v[186:189], v149 offset:3072
	ds_read_b128 v[190:193], v149 offset:4096
	ds_read_b128 v[194:197], v149 offset:5120
	ds_read_b128 v[212:215], v149 offset:6144
	ds_read_b128 v[216:219], v149 offset:7168
	global_load_lds_dwordx4 v[220:221], off
	v_lshl_add_u64 v[220:221], s[30:31], 0, v[136:137]
	s_add_i32 m0, s42, 0xe000
	s_nop 0
	global_load_lds_dwordx4 v[220:221], off
	s_waitcnt vmcnt(8)
	s_waitcnt lgkmcnt(0)
	s_barrier
	s_setprio 1
	s_waitcnt lgkmcnt(0)
	v_mfma_f32_16x16x32_bf16 v[124:127], v[138:141], v[174:177], 0
	v_mfma_f32_16x16x32_bf16 v[116:119], v[150:153], v[174:177], 0
	v_mfma_f32_16x16x32_bf16 v[108:111], v[138:141], v[182:185], 0
	v_mfma_f32_16x16x32_bf16 v[96:99], v[150:153], v[182:185], 0
	v_mfma_f32_16x16x32_bf16 v[88:91], v[138:141], v[190:193], 0
	v_mfma_f32_16x16x32_bf16 v[80:83], v[150:153], v[190:193], 0
	v_mfma_f32_16x16x32_bf16 v[72:75], v[138:141], v[212:215], 0
	v_mfma_f32_16x16x32_bf16 v[64:67], v[150:153], v[212:215], 0
	v_mfma_f32_16x16x32_bf16 v[124:127], v[142:145], v[178:181], v[124:127]
	v_mfma_f32_16x16x32_bf16 v[116:119], v[154:157], v[178:181], v[116:119]
	v_mfma_f32_16x16x32_bf16 v[108:111], v[142:145], v[186:189], v[108:111]
	v_mfma_f32_16x16x32_bf16 v[96:99], v[154:157], v[186:189], v[96:99]
	v_mfma_f32_16x16x32_bf16 v[88:91], v[142:145], v[194:197], v[88:91]
	v_mfma_f32_16x16x32_bf16 v[80:83], v[154:157], v[194:197], v[80:83]
	v_mfma_f32_16x16x32_bf16 v[72:75], v[142:145], v[216:219], v[72:75]
	v_mfma_f32_16x16x32_bf16 v[64:67], v[154:157], v[216:219], v[64:67]
	s_setprio 0
	s_setprio 1
	v_mfma_f32_16x16x32_bf16 v[120:123], v[158:161], v[174:177], 0
	v_mfma_f32_16x16x32_bf16 v[112:115], v[166:169], v[174:177], 0
	v_mfma_f32_16x16x32_bf16 v[104:107], v[158:161], v[182:185], 0
	v_mfma_f32_16x16x32_bf16 v[100:103], v[166:169], v[182:185], 0
	v_mfma_f32_16x16x32_bf16 v[92:95], v[158:161], v[190:193], 0
	v_mfma_f32_16x16x32_bf16 v[84:87], v[166:169], v[190:193], 0
	v_mfma_f32_16x16x32_bf16 v[76:79], v[158:161], v[212:215], 0
	v_mfma_f32_16x16x32_bf16 v[68:71], v[166:169], v[212:215], 0
	v_mfma_f32_16x16x32_bf16 v[120:123], v[162:165], v[178:181], v[120:123]
	v_mfma_f32_16x16x32_bf16 v[112:115], v[170:173], v[178:181], v[112:115]
	v_mfma_f32_16x16x32_bf16 v[104:107], v[162:165], v[186:189], v[104:107]
	v_mfma_f32_16x16x32_bf16 v[100:103], v[170:173], v[186:189], v[100:103]
	v_mfma_f32_16x16x32_bf16 v[92:95], v[162:165], v[194:197], v[92:95]
	v_mfma_f32_16x16x32_bf16 v[84:87], v[170:173], v[194:197], v[84:87]
	v_mfma_f32_16x16x32_bf16 v[76:79], v[162:165], v[216:219], v[76:79]
	v_mfma_f32_16x16x32_bf16 v[68:71], v[170:173], v[216:219], v[68:71]
	s_setprio 0
	s_barrier
	s_add_i32 s0, s59, s40
	v_lshl_add_u64 v[220:221], s[36:37], 0, v[198:199]
	s_mov_b32 m0, s0
	ds_read_b128 v[174:177], v149 offset:16384
	ds_read_b128 v[178:181], v149 offset:17408
	ds_read_b128 v[182:185], v149 offset:18432
	ds_read_b128 v[186:189], v149 offset:19456
	ds_read_b128 v[190:193], v149 offset:20480
	ds_read_b128 v[194:197], v149 offset:21504
	ds_read_b128 v[212:215], v149 offset:22528
	ds_read_b128 v[216:219], v149 offset:23552
	global_load_lds_dwordx4 v[220:221], off
	s_add_i32 m0, s0, 0x2000
	s_add_u32 s0, s36, 0x80000
	v_lshl_add_u64 v[222:223], s[36:37], 0, v[128:129]
	s_addc_u32 s1, s37, 0
	s_add_i32 s59, s63, s40
	global_load_lds_dwordx4 v[222:223], off
	v_lshl_add_u64 v[224:225], s[0:1], 0, v[198:199]
	s_mov_b32 m0, s59
	v_lshl_add_u64 v[226:227], s[38:39], 0, v[130:131]
	global_load_lds_dwordx4 v[224:225], off
	v_lshl_add_u64 v[224:225], s[0:1], 0, v[128:129]
	s_add_i32 m0, s59, 0x2000
	s_nop 0
	global_load_lds_dwordx4 v[224:225], off
	v_lshl_add_u64 v[224:225], s[38:39], 0, v[132:133]
	s_mov_b32 m0, s42
	s_nop 0
	global_load_lds_dwordx4 v[224:225], off
	s_mov_b32 m0, s43
	s_nop 0
	global_load_lds_dwordx4 v[226:227], off
	s_waitcnt vmcnt(8)
	s_waitcnt lgkmcnt(0)
	s_barrier
	s_setprio 1
	s_waitcnt lgkmcnt(0)
	v_mfma_f32_16x16x32_bf16 v[56:59], v[138:141], v[174:177], 0
	v_mfma_f32_16x16x32_bf16 v[48:51], v[150:153], v[174:177], 0
	v_mfma_f32_16x16x32_bf16 v[40:43], v[138:141], v[182:185], 0
	v_mfma_f32_16x16x32_bf16 v[32:35], v[150:153], v[182:185], 0
	v_mfma_f32_16x16x32_bf16 v[24:27], v[138:141], v[190:193], 0
	v_mfma_f32_16x16x32_bf16 v[16:19], v[150:153], v[190:193], 0
	v_mfma_f32_16x16x32_bf16 v[8:11], v[138:141], v[212:215], 0
	v_mfma_f32_16x16x32_bf16 v[0:3], v[150:153], v[212:215], 0
	v_mfma_f32_16x16x32_bf16 v[56:59], v[142:145], v[178:181], v[56:59]
	v_mfma_f32_16x16x32_bf16 v[48:51], v[154:157], v[178:181], v[48:51]
	v_mfma_f32_16x16x32_bf16 v[40:43], v[142:145], v[186:189], v[40:43]
	v_mfma_f32_16x16x32_bf16 v[32:35], v[154:157], v[186:189], v[32:35]
	v_mfma_f32_16x16x32_bf16 v[24:27], v[142:145], v[194:197], v[24:27]
	v_mfma_f32_16x16x32_bf16 v[16:19], v[154:157], v[194:197], v[16:19]
	v_mfma_f32_16x16x32_bf16 v[8:11], v[142:145], v[216:219], v[8:11]
	v_mfma_f32_16x16x32_bf16 v[0:3], v[154:157], v[216:219], v[0:3]
	s_setprio 0
	s_setprio 1
	v_mfma_f32_16x16x32_bf16 v[60:63], v[158:161], v[174:177], 0
	v_mfma_f32_16x16x32_bf16 v[52:55], v[166:169], v[174:177], 0
	v_mfma_f32_16x16x32_bf16 v[44:47], v[158:161], v[182:185], 0
	v_mfma_f32_16x16x32_bf16 v[36:39], v[166:169], v[182:185], 0
	v_mfma_f32_16x16x32_bf16 v[28:31], v[158:161], v[190:193], 0
	v_mfma_f32_16x16x32_bf16 v[20:23], v[166:169], v[190:193], 0
	v_mfma_f32_16x16x32_bf16 v[12:15], v[158:161], v[212:215], 0
	v_mfma_f32_16x16x32_bf16 v[4:7], v[166:169], v[212:215], 0
	v_mfma_f32_16x16x32_bf16 v[60:63], v[162:165], v[178:181], v[60:63]
	v_mfma_f32_16x16x32_bf16 v[52:55], v[170:173], v[178:181], v[52:55]
	v_mfma_f32_16x16x32_bf16 v[44:47], v[162:165], v[186:189], v[44:47]
	v_mfma_f32_16x16x32_bf16 v[36:39], v[170:173], v[186:189], v[36:39]
	v_mfma_f32_16x16x32_bf16 v[28:31], v[162:165], v[194:197], v[28:31]
	v_mfma_f32_16x16x32_bf16 v[20:23], v[170:173], v[194:197], v[20:23]
	v_mfma_f32_16x16x32_bf16 v[12:15], v[162:165], v[216:219], v[12:15]
	v_mfma_f32_16x16x32_bf16 v[4:7], v[170:173], v[216:219], v[4:7]
	s_setprio 0
	s_barrier
	s_add_i32 s59, 0, 0x18000
	s_add_i32 s63, 0, 0x1c000
	v_add_u32_e32 v154, s59, v147
	v_add_u32_e32 v170, s63, v147
	ds_read_b128 v[138:141], v154
	ds_read_b128 v[142:145], v154 offset:1024
	ds_read_b128 v[150:153], v154 offset:2048
	ds_read_b128 v[154:157], v154 offset:3072
	ds_read_b128 v[158:161], v170
	ds_read_b128 v[162:165], v170 offset:1024
	ds_read_b128 v[166:169], v170 offset:2048
	ds_read_b128 v[170:173], v170 offset:3072
	s_add_u32 s0, s38, 0x80000
	s_addc_u32 s1, s39, 0
	s_mov_b32 m0, s44
	v_lshl_add_u64 v[228:229], s[0:1], 0, v[132:133]
	ds_read_b128 v[174:177], v149 offset:32768
	ds_read_b128 v[178:181], v149 offset:33792
	ds_read_b128 v[182:185], v149 offset:34816
	ds_read_b128 v[186:189], v149 offset:35840
	ds_read_b128 v[190:193], v149 offset:36864
	ds_read_b128 v[194:197], v149 offset:37888
	ds_read_b128 v[212:215], v149 offset:38912
	ds_read_b128 v[216:219], v149 offset:39936
	global_load_lds_dwordx4 v[228:229], off
	v_lshl_add_u64 v[228:229], s[0:1], 0, v[130:131]
	s_mov_b32 m0, s45
	s_nop 0
	global_load_lds_dwordx4 v[228:229], off
	s_waitcnt vmcnt(8)
	s_waitcnt lgkmcnt(0)
	s_barrier
	s_setprio 1
	s_waitcnt lgkmcnt(0)
	v_mfma_f32_16x16x32_bf16 v[124:127], v[138:141], v[174:177], v[124:127]
	v_mfma_f32_16x16x32_bf16 v[116:119], v[150:153], v[174:177], v[116:119]
	v_mfma_f32_16x16x32_bf16 v[108:111], v[138:141], v[182:185], v[108:111]
	v_mfma_f32_16x16x32_bf16 v[96:99], v[150:153], v[182:185], v[96:99]
	v_mfma_f32_16x16x32_bf16 v[88:91], v[138:141], v[190:193], v[88:91]
	v_mfma_f32_16x16x32_bf16 v[80:83], v[150:153], v[190:193], v[80:83]
	v_mfma_f32_16x16x32_bf16 v[72:75], v[138:141], v[212:215], v[72:75]
	v_mfma_f32_16x16x32_bf16 v[64:67], v[150:153], v[212:215], v[64:67]
	v_mfma_f32_16x16x32_bf16 v[124:127], v[142:145], v[178:181], v[124:127]
	v_mfma_f32_16x16x32_bf16 v[116:119], v[154:157], v[178:181], v[116:119]
	v_mfma_f32_16x16x32_bf16 v[108:111], v[142:145], v[186:189], v[108:111]
	v_mfma_f32_16x16x32_bf16 v[96:99], v[154:157], v[186:189], v[96:99]
	v_mfma_f32_16x16x32_bf16 v[88:91], v[142:145], v[194:197], v[88:91]
	v_mfma_f32_16x16x32_bf16 v[80:83], v[154:157], v[194:197], v[80:83]
	v_mfma_f32_16x16x32_bf16 v[72:75], v[142:145], v[216:219], v[72:75]
	v_mfma_f32_16x16x32_bf16 v[64:67], v[154:157], v[216:219], v[64:67]
	s_setprio 0
	s_setprio 1
	v_mfma_f32_16x16x32_bf16 v[120:123], v[158:161], v[174:177], v[120:123]
	v_mfma_f32_16x16x32_bf16 v[112:115], v[166:169], v[174:177], v[112:115]
	v_mfma_f32_16x16x32_bf16 v[104:107], v[158:161], v[182:185], v[104:107]
	v_mfma_f32_16x16x32_bf16 v[100:103], v[166:169], v[182:185], v[100:103]
	v_mfma_f32_16x16x32_bf16 v[92:95], v[158:161], v[190:193], v[92:95]
	v_mfma_f32_16x16x32_bf16 v[84:87], v[166:169], v[190:193], v[84:87]
	v_mfma_f32_16x16x32_bf16 v[76:79], v[158:161], v[212:215], v[76:79]
	v_mfma_f32_16x16x32_bf16 v[68:71], v[166:169], v[212:215], v[68:71]
	v_mfma_f32_16x16x32_bf16 v[120:123], v[162:165], v[178:181], v[120:123]
	v_mfma_f32_16x16x32_bf16 v[112:115], v[170:173], v[178:181], v[112:115]
	v_mfma_f32_16x16x32_bf16 v[104:107], v[162:165], v[186:189], v[104:107]
	v_mfma_f32_16x16x32_bf16 v[100:103], v[170:173], v[186:189], v[100:103]
	v_mfma_f32_16x16x32_bf16 v[92:95], v[162:165], v[194:197], v[92:95]
	v_mfma_f32_16x16x32_bf16 v[84:87], v[170:173], v[194:197], v[84:87]
	v_mfma_f32_16x16x32_bf16 v[76:79], v[162:165], v[216:219], v[76:79]
	v_mfma_f32_16x16x32_bf16 v[68:71], v[170:173], v[216:219], v[68:71]
	s_setprio 0
	s_barrier
	s_add_i32 s0, s59, s40
	v_lshl_add_u64 v[220:221], v[220:221], 0, s[54:55]
	s_mov_b32 m0, s0
	ds_read_b128 v[174:177], v149 offset:49152
	ds_read_b128 v[178:181], v149 offset:50176
	ds_read_b128 v[182:185], v149 offset:51200
	ds_read_b128 v[186:189], v149 offset:52224
	ds_read_b128 v[190:193], v149 offset:53248
	ds_read_b128 v[194:197], v149 offset:54272
	ds_read_b128 v[212:215], v149 offset:55296
	ds_read_b128 v[216:219], v149 offset:56320
	global_load_lds_dwordx4 v[220:221], off
	s_add_i32 m0, s0, 0x2000
	s_add_u32 s0, s36, 0x80080
	v_lshl_add_u64 v[220:221], v[222:223], 0, s[54:55]
	s_addc_u32 s1, s37, 0
	s_add_i32 s36, s63, s40
	global_load_lds_dwordx4 v[220:221], off
	v_lshl_add_u64 v[220:221], s[0:1], 0, v[198:199]
	s_mov_b32 m0, s36
	s_nop 0
	global_load_lds_dwordx4 v[220:221], off
	v_lshl_add_u64 v[220:221], s[0:1], 0, v[128:129]
	s_add_i32 m0, s36, 0x2000
	s_nop 0
	global_load_lds_dwordx4 v[220:221], off
	v_lshl_add_u64 v[220:221], v[224:225], 0, s[54:55]
	s_mov_b32 m0, s47
	s_nop 0
	global_load_lds_dwordx4 v[220:221], off
	v_lshl_add_u64 v[220:221], v[226:227], 0, s[54:55]
	s_mov_b32 m0, s48
	s_nop 0
	global_load_lds_dwordx4 v[220:221], off
	s_waitcnt vmcnt(8)
	s_waitcnt lgkmcnt(0)
	s_barrier
	s_setprio 1
	s_waitcnt lgkmcnt(0)
	v_mfma_f32_16x16x32_bf16 v[56:59], v[138:141], v[174:177], v[56:59]
	v_mfma_f32_16x16x32_bf16 v[48:51], v[150:153], v[174:177], v[48:51]
	v_mfma_f32_16x16x32_bf16 v[40:43], v[138:141], v[182:185], v[40:43]
	v_mfma_f32_16x16x32_bf16 v[32:35], v[150:153], v[182:185], v[32:35]
	v_mfma_f32_16x16x32_bf16 v[24:27], v[138:141], v[190:193], v[24:27]
	v_mfma_f32_16x16x32_bf16 v[16:19], v[150:153], v[190:193], v[16:19]
	v_mfma_f32_16x16x32_bf16 v[8:11], v[138:141], v[212:215], v[8:11]
	v_mfma_f32_16x16x32_bf16 v[0:3], v[150:153], v[212:215], v[0:3]
	v_mfma_f32_16x16x32_bf16 v[56:59], v[142:145], v[178:181], v[56:59]
	v_mfma_f32_16x16x32_bf16 v[48:51], v[154:157], v[178:181], v[48:51]
	v_mfma_f32_16x16x32_bf16 v[40:43], v[142:145], v[186:189], v[40:43]
	v_mfma_f32_16x16x32_bf16 v[32:35], v[154:157], v[186:189], v[32:35]
	v_mfma_f32_16x16x32_bf16 v[24:27], v[142:145], v[194:197], v[24:27]
	v_mfma_f32_16x16x32_bf16 v[16:19], v[154:157], v[194:197], v[16:19]
	v_mfma_f32_16x16x32_bf16 v[8:11], v[142:145], v[216:219], v[8:11]
	v_mfma_f32_16x16x32_bf16 v[0:3], v[154:157], v[216:219], v[0:3]
	s_setprio 0
	s_setprio 1
	v_mfma_f32_16x16x32_bf16 v[60:63], v[158:161], v[174:177], v[60:63]
	v_mfma_f32_16x16x32_bf16 v[52:55], v[166:169], v[174:177], v[52:55]
	v_mfma_f32_16x16x32_bf16 v[44:47], v[158:161], v[182:185], v[44:47]
	v_mfma_f32_16x16x32_bf16 v[36:39], v[166:169], v[182:185], v[36:39]
	v_mfma_f32_16x16x32_bf16 v[28:31], v[158:161], v[190:193], v[28:31]
	v_mfma_f32_16x16x32_bf16 v[20:23], v[166:169], v[190:193], v[20:23]
	v_mfma_f32_16x16x32_bf16 v[12:15], v[158:161], v[212:215], v[12:15]
	v_mfma_f32_16x16x32_bf16 v[4:7], v[166:169], v[212:215], v[4:7]
	v_mfma_f32_16x16x32_bf16 v[60:63], v[162:165], v[178:181], v[60:63]
	v_mfma_f32_16x16x32_bf16 v[52:55], v[170:173], v[178:181], v[52:55]
	v_mfma_f32_16x16x32_bf16 v[44:47], v[162:165], v[186:189], v[44:47]
	v_mfma_f32_16x16x32_bf16 v[36:39], v[170:173], v[186:189], v[36:39]
	v_mfma_f32_16x16x32_bf16 v[28:31], v[162:165], v[194:197], v[28:31]
	v_mfma_f32_16x16x32_bf16 v[20:23], v[170:173], v[194:197], v[20:23]
	v_mfma_f32_16x16x32_bf16 v[12:15], v[162:165], v[216:219], v[12:15]
	v_mfma_f32_16x16x32_bf16 v[4:7], v[170:173], v[216:219], v[4:7]
	s_setprio 0
	s_barrier
	s_add_i32 s61, s61, 2
	s_add_u32 s30, s30, 0x100
	s_addc_u32 s31, s31, 0
	s_add_u32 s35, s35, 0x100
	s_addc_u32 s52, s52, 0
